# all per-phase s_setprio 1/0 flips removed from the four 8-phase GEMM K-loops (static-priority lever: plain equal priority measured best)
# speedup vs baseline: 1.0117x; 1.0069x over previous
.LBB0_362:
	v_add_u32_e32 v144, s77, v137
	ds_read_b128 v[146:149], v144
	ds_read_b128 v[150:153], v144 offset:1024
	ds_read_b128 v[154:157], v144 offset:2048
	ds_read_b128 v[158:161], v144 offset:3072
	s_add_u32 s49, s36, s38
	s_addc_u32 s52, s37, s39
	s_add_u32 s50, s49, 0x80
	s_addc_u32 s51, s52, 0
	v_add_u32_e32 v144, 0xc000, v131
	v_lshl_add_u64 v[190:191], s[50:51], 0, v[192:193]
	v_readfirstlane_b32 s50, v144
	v_add_u32_e32 v145, 0xe000, v131
	s_mov_b32 m0, s50
	v_readfirstlane_b32 s50, v145
	ds_read_b128 v[162:165], v128
	ds_read_b128 v[166:169], v128 offset:1024
	ds_read_b128 v[170:173], v128 offset:2048
	ds_read_b128 v[174:177], v128 offset:3072
	ds_read_b128 v[178:181], v128 offset:4096
	ds_read_b128 v[182:185], v128 offset:5120
	ds_read_b128 v[186:189], v128 offset:6144
	ds_read_b128 v[196:199], v128 offset:7168
	global_load_lds_dwordx4 v[190:191], off
	v_lshl_add_u64 v[190:191], v[190:191], 0, s[4:5]
	s_mov_b32 m0, s50
	s_nop 0
	global_load_lds_dwordx4 v[190:191], off
	s_waitcnt lgkmcnt(8)
	s_barrier
	s_waitcnt lgkmcnt(0)
	s_waitcnt lgkmcnt(0)
	v_mfma_f32_16x16x32_bf16 v[124:127], v[162:165], v[146:149], v[124:127]
	v_mfma_f32_16x16x32_bf16 v[120:123], v[162:165], v[154:157], v[120:123]
	v_mfma_f32_16x16x32_bf16 v[116:119], v[170:173], v[146:149], v[116:119]
	v_mfma_f32_16x16x32_bf16 v[112:115], v[170:173], v[154:157], v[112:115]
	v_mfma_f32_16x16x32_bf16 v[108:111], v[178:181], v[146:149], v[108:111]
	v_mfma_f32_16x16x32_bf16 v[104:107], v[178:181], v[154:157], v[104:107]
	v_mfma_f32_16x16x32_bf16 v[100:103], v[186:189], v[146:149], v[100:103]
	v_mfma_f32_16x16x32_bf16 v[96:99], v[186:189], v[154:157], v[96:99]
	v_mfma_f32_16x16x32_bf16 v[124:127], v[166:169], v[150:153], v[124:127]
	v_mfma_f32_16x16x32_bf16 v[120:123], v[166:169], v[158:161], v[120:123]
	v_mfma_f32_16x16x32_bf16 v[116:119], v[174:177], v[150:153], v[116:119]
	v_mfma_f32_16x16x32_bf16 v[112:115], v[174:177], v[158:161], v[112:115]
	v_mfma_f32_16x16x32_bf16 v[108:111], v[182:185], v[150:153], v[108:111]
	v_mfma_f32_16x16x32_bf16 v[104:107], v[182:185], v[158:161], v[104:107]
	v_mfma_f32_16x16x32_bf16 v[100:103], v[196:199], v[150:153], v[100:103]
	v_mfma_f32_16x16x32_bf16 v[96:99], v[196:199], v[158:161], v[96:99]
	s_barrier
	s_add_u32 s53, s0, s38
	s_addc_u32 s54, s1, s39
	s_add_u32 s50, s53, 0x100
	v_add_u32_e32 v190, s33, v137
	s_addc_u32 s51, s54, 0
	ds_read_b128 v[200:203], v190
	ds_read_b128 v[204:207], v190 offset:1024
	ds_read_b128 v[208:211], v190 offset:2048
	ds_read_b128 v[212:215], v190 offset:3072
	v_lshl_add_u64 v[190:191], s[50:51], 0, v[192:193]
	v_readfirstlane_b32 s50, v129
	s_mov_b32 m0, s50
	v_readfirstlane_b32 s50, v130
	global_load_lds_dwordx4 v[190:191], off
	v_lshl_add_u64 v[190:191], v[190:191], 0, s[4:5]
	s_mov_b32 m0, s50
	s_nop 0
	global_load_lds_dwordx4 v[190:191], off
	s_barrier
	s_waitcnt lgkmcnt(0)
	s_waitcnt lgkmcnt(0)
	v_mfma_f32_16x16x32_bf16 v[92:95], v[162:165], v[200:203], v[92:95]
	v_mfma_f32_16x16x32_bf16 v[88:91], v[162:165], v[208:211], v[88:91]
	v_mfma_f32_16x16x32_bf16 v[84:87], v[170:173], v[200:203], v[84:87]
	v_mfma_f32_16x16x32_bf16 v[80:83], v[170:173], v[208:211], v[80:83]
	v_mfma_f32_16x16x32_bf16 v[76:79], v[178:181], v[200:203], v[76:79]
	v_mfma_f32_16x16x32_bf16 v[72:75], v[178:181], v[208:211], v[72:75]
	v_mfma_f32_16x16x32_bf16 v[68:71], v[186:189], v[200:203], v[68:71]
	v_mfma_f32_16x16x32_bf16 v[64:67], v[186:189], v[208:211], v[64:67]
	v_mfma_f32_16x16x32_bf16 v[92:95], v[166:169], v[204:207], v[92:95]
	v_mfma_f32_16x16x32_bf16 v[88:91], v[166:169], v[212:215], v[88:91]
	v_mfma_f32_16x16x32_bf16 v[84:87], v[174:177], v[204:207], v[84:87]
	v_mfma_f32_16x16x32_bf16 v[80:83], v[174:177], v[212:215], v[80:83]
	v_mfma_f32_16x16x32_bf16 v[76:79], v[182:185], v[204:207], v[76:79]
	v_mfma_f32_16x16x32_bf16 v[72:75], v[182:185], v[212:215], v[72:75]
	v_mfma_f32_16x16x32_bf16 v[68:71], v[196:199], v[204:207], v[68:71]
	v_mfma_f32_16x16x32_bf16 v[64:67], v[196:199], v[212:215], v[64:67]
	s_add_u32 s55, s2, s38
	s_addc_u32 s72, s3, s39
	s_add_u32 s50, s55, 0x100
	s_addc_u32 s51, s72, 0
	v_lshl_add_u64 v[190:191], s[50:51], 0, v[192:193]
	v_readfirstlane_b32 s50, v131
	s_mov_b32 m0, s50
	v_readfirstlane_b32 s50, v132
	s_barrier
	ds_read_b128 v[162:165], v128 offset:16384
	ds_read_b128 v[166:169], v128 offset:17408
	ds_read_b128 v[170:173], v128 offset:18432
	ds_read_b128 v[174:177], v128 offset:19456
	ds_read_b128 v[178:181], v128 offset:20480
	ds_read_b128 v[182:185], v128 offset:21504
	ds_read_b128 v[186:189], v128 offset:22528
	ds_read_b128 v[196:199], v128 offset:23552
	global_load_lds_dwordx4 v[190:191], off
	v_lshl_add_u64 v[190:191], v[190:191], 0, s[4:5]
	s_mov_b32 m0, s50
	s_nop 0
	global_load_lds_dwordx4 v[190:191], off
	s_barrier
	s_waitcnt lgkmcnt(0)
	s_waitcnt lgkmcnt(0)
	v_mfma_f32_16x16x32_bf16 v[60:63], v[162:165], v[146:149], v[60:63]
	v_mfma_f32_16x16x32_bf16 v[56:59], v[162:165], v[154:157], v[56:59]
	v_mfma_f32_16x16x32_bf16 v[52:55], v[170:173], v[146:149], v[52:55]
	v_mfma_f32_16x16x32_bf16 v[48:51], v[170:173], v[154:157], v[48:51]
	v_mfma_f32_16x16x32_bf16 v[44:47], v[178:181], v[146:149], v[44:47]
	v_mfma_f32_16x16x32_bf16 v[40:43], v[178:181], v[154:157], v[40:43]
	v_mfma_f32_16x16x32_bf16 v[36:39], v[186:189], v[146:149], v[36:39]
	v_mfma_f32_16x16x32_bf16 v[32:35], v[186:189], v[154:157], v[32:35]
	v_mfma_f32_16x16x32_bf16 v[60:63], v[166:169], v[150:153], v[60:63]
	v_mfma_f32_16x16x32_bf16 v[56:59], v[166:169], v[158:161], v[56:59]
	v_mfma_f32_16x16x32_bf16 v[52:55], v[174:177], v[150:153], v[52:55]
	v_mfma_f32_16x16x32_bf16 v[48:51], v[174:177], v[158:161], v[48:51]
	v_mfma_f32_16x16x32_bf16 v[44:47], v[182:185], v[150:153], v[44:47]
	v_mfma_f32_16x16x32_bf16 v[40:43], v[182:185], v[158:161], v[40:43]
	v_mfma_f32_16x16x32_bf16 v[36:39], v[196:199], v[150:153], v[36:39]
	v_mfma_f32_16x16x32_bf16 v[32:35], v[196:199], v[158:161], v[32:35]
	s_barrier
	s_add_u32 s73, s12, s38
	s_addc_u32 s74, s13, s39
	s_add_u32 s50, s73, 0x100
	s_addc_u32 s51, s74, 0
	v_lshl_add_u64 v[146:147], s[50:51], 0, v[192:193]
	v_readfirstlane_b32 s50, v133
	s_mov_b32 m0, s50
	v_readfirstlane_b32 s50, v134
	global_load_lds_dwordx4 v[146:147], off
	v_lshl_add_u64 v[146:147], v[146:147], 0, s[4:5]
	s_mov_b32 m0, s50
	s_nop 0
	global_load_lds_dwordx4 v[146:147], off
	s_waitcnt vmcnt(6)
	s_barrier
	v_mfma_f32_16x16x32_bf16 v[28:31], v[162:165], v[200:203], v[28:31]
	v_mfma_f32_16x16x32_bf16 v[24:27], v[162:165], v[208:211], v[24:27]
	v_mfma_f32_16x16x32_bf16 v[20:23], v[170:173], v[200:203], v[20:23]
	v_mfma_f32_16x16x32_bf16 v[16:19], v[170:173], v[208:211], v[16:19]
	v_mfma_f32_16x16x32_bf16 v[12:15], v[178:181], v[200:203], v[12:15]
	v_mfma_f32_16x16x32_bf16 v[8:11], v[178:181], v[208:211], v[8:11]
	v_mfma_f32_16x16x32_bf16 v[4:7], v[186:189], v[200:203], v[4:7]
	v_mfma_f32_16x16x32_bf16 v[0:3], v[186:189], v[208:211], v[0:3]
	v_mfma_f32_16x16x32_bf16 v[28:31], v[166:169], v[204:207], v[28:31]
	v_mfma_f32_16x16x32_bf16 v[24:27], v[166:169], v[212:215], v[24:27]
	v_mfma_f32_16x16x32_bf16 v[20:23], v[174:177], v[204:207], v[20:23]
	v_mfma_f32_16x16x32_bf16 v[16:19], v[174:177], v[212:215], v[16:19]
	v_mfma_f32_16x16x32_bf16 v[12:15], v[182:185], v[204:207], v[12:15]
	v_mfma_f32_16x16x32_bf16 v[8:11], v[182:185], v[212:215], v[8:11]
	v_mfma_f32_16x16x32_bf16 v[4:7], v[196:199], v[204:207], v[4:7]
	v_mfma_f32_16x16x32_bf16 v[0:3], v[196:199], v[212:215], v[0:3]
	v_add_u32_e32 v158, s93, v137
	s_barrier
	ds_read_b128 v[146:149], v158
	ds_read_b128 v[150:153], v158 offset:1024
	ds_read_b128 v[154:157], v158 offset:2048
	ds_read_b128 v[158:161], v158 offset:3072
	s_add_u32 s50, s49, 0x100
	s_addc_u32 s51, s52, 0
	v_readfirstlane_b32 s49, v135
	v_lshl_add_u64 v[190:191], s[50:51], 0, v[192:193]
	s_mov_b32 m0, s49
	v_readfirstlane_b32 s49, v136
	ds_read_b128 v[162:165], v128 offset:32768
	ds_read_b128 v[166:169], v128 offset:33792
	ds_read_b128 v[170:173], v128 offset:34816
	ds_read_b128 v[174:177], v128 offset:35840
	ds_read_b128 v[178:181], v128 offset:36864
	ds_read_b128 v[182:185], v128 offset:37888
	ds_read_b128 v[186:189], v128 offset:38912
	ds_read_b128 v[196:199], v128 offset:39936
	global_load_lds_dwordx4 v[190:191], off
	v_lshl_add_u64 v[190:191], v[190:191], 0, s[4:5]
	s_mov_b32 m0, s49
	s_nop 0
	global_load_lds_dwordx4 v[190:191], off
	s_waitcnt lgkmcnt(8)
	s_barrier
	s_waitcnt lgkmcnt(0)
	s_waitcnt lgkmcnt(0)
	v_mfma_f32_16x16x32_bf16 v[124:127], v[162:165], v[146:149], v[124:127]
	v_mfma_f32_16x16x32_bf16 v[120:123], v[162:165], v[154:157], v[120:123]
	v_mfma_f32_16x16x32_bf16 v[116:119], v[170:173], v[146:149], v[116:119]
	v_mfma_f32_16x16x32_bf16 v[112:115], v[170:173], v[154:157], v[112:115]
	v_mfma_f32_16x16x32_bf16 v[108:111], v[178:181], v[146:149], v[108:111]
	v_mfma_f32_16x16x32_bf16 v[104:107], v[178:181], v[154:157], v[104:107]
	v_mfma_f32_16x16x32_bf16 v[100:103], v[186:189], v[146:149], v[100:103]
	v_mfma_f32_16x16x32_bf16 v[96:99], v[186:189], v[154:157], v[96:99]
	v_mfma_f32_16x16x32_bf16 v[124:127], v[166:169], v[150:153], v[124:127]
	v_mfma_f32_16x16x32_bf16 v[120:123], v[166:169], v[158:161], v[120:123]
	v_mfma_f32_16x16x32_bf16 v[116:119], v[174:177], v[150:153], v[116:119]
	v_mfma_f32_16x16x32_bf16 v[112:115], v[174:177], v[158:161], v[112:115]
	v_mfma_f32_16x16x32_bf16 v[108:111], v[182:185], v[150:153], v[108:111]
	v_mfma_f32_16x16x32_bf16 v[104:107], v[182:185], v[158:161], v[104:107]
	v_mfma_f32_16x16x32_bf16 v[100:103], v[196:199], v[150:153], v[100:103]
	v_mfma_f32_16x16x32_bf16 v[96:99], v[196:199], v[158:161], v[96:99]
	s_barrier
	s_add_u32 s50, s53, 0x180
	v_add_u32_e32 v190, s89, v137
	s_addc_u32 s51, s54, 0
	v_readfirstlane_b32 s49, v138
	ds_read_b128 v[200:203], v190
	ds_read_b128 v[204:207], v190 offset:1024
	ds_read_b128 v[208:211], v190 offset:2048
	ds_read_b128 v[212:215], v190 offset:3072
	v_lshl_add_u64 v[190:191], s[50:51], 0, v[192:193]
	s_mov_b32 m0, s49
	v_readfirstlane_b32 s49, v139
	global_load_lds_dwordx4 v[190:191], off
	v_lshl_add_u64 v[190:191], v[190:191], 0, s[4:5]
	s_mov_b32 m0, s49
	s_nop 0
	global_load_lds_dwordx4 v[190:191], off
	s_barrier
	s_waitcnt lgkmcnt(0)
	s_waitcnt lgkmcnt(0)
	v_mfma_f32_16x16x32_bf16 v[92:95], v[162:165], v[200:203], v[92:95]
	v_mfma_f32_16x16x32_bf16 v[88:91], v[162:165], v[208:211], v[88:91]
	v_mfma_f32_16x16x32_bf16 v[84:87], v[170:173], v[200:203], v[84:87]
	v_mfma_f32_16x16x32_bf16 v[80:83], v[170:173], v[208:211], v[80:83]
	v_mfma_f32_16x16x32_bf16 v[76:79], v[178:181], v[200:203], v[76:79]
	v_mfma_f32_16x16x32_bf16 v[72:75], v[178:181], v[208:211], v[72:75]
	v_mfma_f32_16x16x32_bf16 v[68:71], v[186:189], v[200:203], v[68:71]
	v_mfma_f32_16x16x32_bf16 v[64:67], v[186:189], v[208:211], v[64:67]
	v_mfma_f32_16x16x32_bf16 v[92:95], v[166:169], v[204:207], v[92:95]
	v_mfma_f32_16x16x32_bf16 v[88:91], v[166:169], v[212:215], v[88:91]
	v_mfma_f32_16x16x32_bf16 v[84:87], v[174:177], v[204:207], v[84:87]
	v_mfma_f32_16x16x32_bf16 v[80:83], v[174:177], v[212:215], v[80:83]
	v_mfma_f32_16x16x32_bf16 v[76:79], v[182:185], v[204:207], v[76:79]
	v_mfma_f32_16x16x32_bf16 v[72:75], v[182:185], v[212:215], v[72:75]
	v_mfma_f32_16x16x32_bf16 v[68:71], v[196:199], v[204:207], v[68:71]
	v_mfma_f32_16x16x32_bf16 v[64:67], v[196:199], v[212:215], v[64:67]
	s_add_u32 s50, s55, 0x180
	s_addc_u32 s51, s72, 0
	v_readfirstlane_b32 s49, v140
	v_lshl_add_u64 v[190:191], s[50:51], 0, v[192:193]
	s_mov_b32 m0, s49
	v_readfirstlane_b32 s49, v141
	s_barrier
	ds_read_b128 v[162:165], v128 offset:49152
	ds_read_b128 v[166:169], v128 offset:50176
	ds_read_b128 v[170:173], v128 offset:51200
	ds_read_b128 v[174:177], v128 offset:52224
	ds_read_b128 v[178:181], v128 offset:53248
	ds_read_b128 v[182:185], v128 offset:54272
	ds_read_b128 v[186:189], v128 offset:55296
	ds_read_b128 v[196:199], v128 offset:56320
	global_load_lds_dwordx4 v[190:191], off
	v_lshl_add_u64 v[190:191], v[190:191], 0, s[4:5]
	s_mov_b32 m0, s49
	s_nop 0
	global_load_lds_dwordx4 v[190:191], off
	s_barrier
	s_waitcnt lgkmcnt(0)
	s_waitcnt lgkmcnt(0)
	v_mfma_f32_16x16x32_bf16 v[60:63], v[162:165], v[146:149], v[60:63]
	v_mfma_f32_16x16x32_bf16 v[56:59], v[162:165], v[154:157], v[56:59]
	v_mfma_f32_16x16x32_bf16 v[52:55], v[170:173], v[146:149], v[52:55]
	v_mfma_f32_16x16x32_bf16 v[48:51], v[170:173], v[154:157], v[48:51]
	v_mfma_f32_16x16x32_bf16 v[44:47], v[178:181], v[146:149], v[44:47]
	v_mfma_f32_16x16x32_bf16 v[40:43], v[178:181], v[154:157], v[40:43]
	v_mfma_f32_16x16x32_bf16 v[36:39], v[186:189], v[146:149], v[36:39]
	v_mfma_f32_16x16x32_bf16 v[32:35], v[186:189], v[154:157], v[32:35]
	v_mfma_f32_16x16x32_bf16 v[60:63], v[166:169], v[150:153], v[60:63]
	v_mfma_f32_16x16x32_bf16 v[56:59], v[166:169], v[158:161], v[56:59]
	v_mfma_f32_16x16x32_bf16 v[52:55], v[174:177], v[150:153], v[52:55]
	v_mfma_f32_16x16x32_bf16 v[48:51], v[174:177], v[158:161], v[48:51]
	v_mfma_f32_16x16x32_bf16 v[44:47], v[182:185], v[150:153], v[44:47]
	v_mfma_f32_16x16x32_bf16 v[40:43], v[182:185], v[158:161], v[40:43]
	v_mfma_f32_16x16x32_bf16 v[36:39], v[196:199], v[150:153], v[36:39]
	v_mfma_f32_16x16x32_bf16 v[32:35], v[196:199], v[158:161], v[32:35]
	s_barrier
	s_add_u32 s50, s73, 0x180
	s_addc_u32 s51, s74, 0
	v_readfirstlane_b32 s49, v142
	v_lshl_add_u64 v[146:147], s[50:51], 0, v[192:193]
	s_mov_b32 m0, s49
	v_readfirstlane_b32 s49, v143
	global_load_lds_dwordx4 v[146:147], off
	v_lshl_add_u64 v[146:147], v[146:147], 0, s[4:5]
	s_mov_b32 m0, s49
	s_nop 0
	global_load_lds_dwordx4 v[146:147], off
	s_waitcnt vmcnt(6)
	s_barrier
	v_mfma_f32_16x16x32_bf16 v[28:31], v[162:165], v[200:203], v[28:31]
	v_mfma_f32_16x16x32_bf16 v[24:27], v[162:165], v[208:211], v[24:27]
	v_mfma_f32_16x16x32_bf16 v[20:23], v[170:173], v[200:203], v[20:23]
	v_mfma_f32_16x16x32_bf16 v[16:19], v[170:173], v[208:211], v[16:19]
	v_mfma_f32_16x16x32_bf16 v[12:15], v[178:181], v[200:203], v[12:15]
	v_mfma_f32_16x16x32_bf16 v[8:11], v[178:181], v[208:211], v[8:11]
	v_mfma_f32_16x16x32_bf16 v[4:7], v[186:189], v[200:203], v[4:7]
	v_mfma_f32_16x16x32_bf16 v[0:3], v[186:189], v[208:211], v[0:3]
	v_mfma_f32_16x16x32_bf16 v[28:31], v[166:169], v[204:207], v[28:31]
	v_mfma_f32_16x16x32_bf16 v[24:27], v[166:169], v[212:215], v[24:27]
	v_mfma_f32_16x16x32_bf16 v[20:23], v[174:177], v[204:207], v[20:23]
	v_mfma_f32_16x16x32_bf16 v[16:19], v[174:177], v[212:215], v[16:19]
	v_mfma_f32_16x16x32_bf16 v[12:15], v[182:185], v[204:207], v[12:15]
	v_mfma_f32_16x16x32_bf16 v[8:11], v[182:185], v[212:215], v[8:11]
	v_mfma_f32_16x16x32_bf16 v[4:7], v[196:199], v[204:207], v[4:7]
	v_mfma_f32_16x16x32_bf16 v[0:3], v[196:199], v[212:215], v[0:3]
	s_add_i32 s48, s48, 2
	s_add_u32 s38, s38, 0x100
	s_addc_u32 s39, s39, 0
	s_cmp_lt_u32 s48, 12
	s_barrier
	s_cbranch_scc1 .LBB0_362
	v_add_u32_e32 v129, 0, v137
	s_add_u32 s0, s36, 0x780
	v_add_u32_e32 v142, 0x10000, v129
	s_addc_u32 s1, s37, 0
	ds_read_b128 v[130:133], v142
	ds_read_b128 v[134:137], v142 offset:1024
	ds_read_b128 v[138:141], v142 offset:2048
	ds_read_b128 v[146:149], v142 offset:3072
	ds_read_b128 v[150:153], v128
	ds_read_b128 v[154:157], v128 offset:1024
	ds_read_b128 v[158:161], v128 offset:2048
	ds_read_b128 v[162:165], v128 offset:3072
	ds_read_b128 v[166:169], v128 offset:4096
	ds_read_b128 v[170:173], v128 offset:5120
	ds_read_b128 v[174:177], v128 offset:6144
	ds_read_b128 v[178:181], v128 offset:7168
	v_lshl_add_u64 v[142:143], s[0:1], 0, v[192:193]
	v_readfirstlane_b32 s0, v144
	s_mov_b32 m0, s0
	v_readfirstlane_b32 s0, v145
	global_load_lds_dwordx4 v[142:143], off
	v_lshl_add_u64 v[142:143], v[142:143], 0, s[4:5]
	s_mov_b32 m0, s0
	s_nop 0
	global_load_lds_dwordx4 v[142:143], off
	s_barrier
	s_waitcnt lgkmcnt(0)
	s_waitcnt lgkmcnt(0)
	v_mfma_f32_16x16x32_bf16 v[124:127], v[150:153], v[130:133], v[124:127]
	v_mfma_f32_16x16x32_bf16 v[120:123], v[150:153], v[138:141], v[120:123]
	v_mfma_f32_16x16x32_bf16 v[116:119], v[158:161], v[130:133], v[116:119]
	v_mfma_f32_16x16x32_bf16 v[112:115], v[158:161], v[138:141], v[112:115]
	v_mfma_f32_16x16x32_bf16 v[108:111], v[166:169], v[130:133], v[108:111]
	v_mfma_f32_16x16x32_bf16 v[104:107], v[166:169], v[138:141], v[104:107]
	v_mfma_f32_16x16x32_bf16 v[100:103], v[174:177], v[130:133], v[100:103]
	v_mfma_f32_16x16x32_bf16 v[96:99], v[174:177], v[138:141], v[96:99]
	v_mfma_f32_16x16x32_bf16 v[124:127], v[154:157], v[134:137], v[124:127]
	v_mfma_f32_16x16x32_bf16 v[120:123], v[154:157], v[146:149], v[120:123]
	v_mfma_f32_16x16x32_bf16 v[116:119], v[162:165], v[134:137], v[116:119]
	v_mfma_f32_16x16x32_bf16 v[112:115], v[162:165], v[146:149], v[112:115]
	v_mfma_f32_16x16x32_bf16 v[108:111], v[170:173], v[134:137], v[108:111]
	v_mfma_f32_16x16x32_bf16 v[104:107], v[170:173], v[146:149], v[104:107]
	v_mfma_f32_16x16x32_bf16 v[100:103], v[178:181], v[134:137], v[100:103]
	v_mfma_f32_16x16x32_bf16 v[96:99], v[178:181], v[146:149], v[96:99]
	v_add_u32_e32 v190, 0x14000, v129
	s_barrier
	ds_read_b128 v[142:145], v190
	ds_read_b128 v[182:185], v190 offset:1024
	ds_read_b128 v[186:189], v190 offset:2048
	ds_read_b128 v[196:199], v190 offset:3072
	s_barrier
	s_waitcnt lgkmcnt(0)
	s_waitcnt lgkmcnt(0)
	v_mfma_f32_16x16x32_bf16 v[92:95], v[150:153], v[142:145], v[92:95]
	v_mfma_f32_16x16x32_bf16 v[88:91], v[150:153], v[186:189], v[88:91]
	v_mfma_f32_16x16x32_bf16 v[84:87], v[158:161], v[142:145], v[84:87]
	v_mfma_f32_16x16x32_bf16 v[80:83], v[158:161], v[186:189], v[80:83]
	v_mfma_f32_16x16x32_bf16 v[76:79], v[166:169], v[142:145], v[76:79]
	v_mfma_f32_16x16x32_bf16 v[72:75], v[166:169], v[186:189], v[72:75]
	v_mfma_f32_16x16x32_bf16 v[68:71], v[174:177], v[142:145], v[68:71]
	v_mfma_f32_16x16x32_bf16 v[64:67], v[174:177], v[186:189], v[64:67]
	v_mfma_f32_16x16x32_bf16 v[200:203], v[154:157], v[182:185], v[92:95]
	v_mfma_f32_16x16x32_bf16 v[150:153], v[154:157], v[196:199], v[88:91]
	v_mfma_f32_16x16x32_bf16 v[154:157], v[162:165], v[182:185], v[84:87]
	v_mfma_f32_16x16x32_bf16 v[158:161], v[162:165], v[196:199], v[80:83]
	v_mfma_f32_16x16x32_bf16 v[162:165], v[170:173], v[182:185], v[76:79]
	v_mfma_f32_16x16x32_bf16 v[166:169], v[170:173], v[196:199], v[72:75]
	v_mfma_f32_16x16x32_bf16 v[170:173], v[178:181], v[182:185], v[68:71]
	v_mfma_f32_16x16x32_bf16 v[174:177], v[178:181], v[196:199], v[64:67]
	s_barrier
	s_nop 0
	ds_read_b128 v[64:67], v128 offset:16384
	ds_read_b128 v[68:71], v128 offset:17408
	ds_read_b128 v[72:75], v128 offset:18432
	ds_read_b128 v[76:79], v128 offset:19456
	ds_read_b128 v[80:83], v128 offset:20480
	ds_read_b128 v[84:87], v128 offset:21504
	ds_read_b128 v[88:91], v128 offset:22528
	ds_read_b128 v[92:95], v128 offset:23552
	s_waitcnt vmcnt(4)
	s_barrier
	s_waitcnt lgkmcnt(0)
	s_waitcnt lgkmcnt(0)
	v_mfma_f32_16x16x32_bf16 v[60:63], v[64:67], v[130:133], v[60:63]
	v_mfma_f32_16x16x32_bf16 v[56:59], v[64:67], v[138:141], v[56:59]
	v_mfma_f32_16x16x32_bf16 v[52:55], v[72:75], v[130:133], v[52:55]
	v_mfma_f32_16x16x32_bf16 v[48:51], v[72:75], v[138:141], v[48:51]
	v_mfma_f32_16x16x32_bf16 v[44:47], v[80:83], v[130:133], v[44:47]
	v_mfma_f32_16x16x32_bf16 v[40:43], v[80:83], v[138:141], v[40:43]
	v_mfma_f32_16x16x32_bf16 v[36:39], v[88:91], v[130:133], v[36:39]
	v_mfma_f32_16x16x32_bf16 v[32:35], v[88:91], v[138:141], v[32:35]
	v_mfma_f32_16x16x32_bf16 v[60:63], v[68:71], v[134:137], v[60:63]
	v_mfma_f32_16x16x32_bf16 v[56:59], v[68:71], v[146:149], v[56:59]
	v_mfma_f32_16x16x32_bf16 v[52:55], v[76:79], v[134:137], v[52:55]
	v_mfma_f32_16x16x32_bf16 v[48:51], v[76:79], v[146:149], v[48:51]
	v_mfma_f32_16x16x32_bf16 v[44:47], v[84:87], v[134:137], v[44:47]
	v_mfma_f32_16x16x32_bf16 v[40:43], v[84:87], v[146:149], v[40:43]
	v_mfma_f32_16x16x32_bf16 v[36:39], v[92:95], v[134:137], v[36:39]
	v_mfma_f32_16x16x32_bf16 v[32:35], v[92:95], v[146:149], v[32:35]
	v_mfma_f32_16x16x32_bf16 v[28:31], v[64:67], v[142:145], v[28:31]
	v_mfma_f32_16x16x32_bf16 v[24:27], v[64:67], v[186:189], v[24:27]
	v_mfma_f32_16x16x32_bf16 v[20:23], v[72:75], v[142:145], v[20:23]
	v_mfma_f32_16x16x32_bf16 v[16:19], v[72:75], v[186:189], v[16:19]
	v_mfma_f32_16x16x32_bf16 v[12:15], v[80:83], v[142:145], v[12:15]
	v_mfma_f32_16x16x32_bf16 v[8:11], v[80:83], v[186:189], v[8:11]
	v_mfma_f32_16x16x32_bf16 v[4:7], v[88:91], v[142:145], v[4:7]
	v_mfma_f32_16x16x32_bf16 v[0:3], v[88:91], v[186:189], v[0:3]
	v_mfma_f32_16x16x32_bf16 v[130:133], v[68:71], v[182:185], v[28:31]
	v_mfma_f32_16x16x32_bf16 v[134:137], v[68:71], v[196:199], v[24:27]
	v_mfma_f32_16x16x32_bf16 v[138:141], v[76:79], v[182:185], v[20:23]
	v_mfma_f32_16x16x32_bf16 v[146:149], v[76:79], v[196:199], v[16:19]
	v_mfma_f32_16x16x32_bf16 v[178:181], v[84:87], v[182:185], v[12:15]
	v_mfma_f32_16x16x32_bf16 v[204:207], v[84:87], v[196:199], v[8:11]
	v_mfma_f32_16x16x32_bf16 v[142:145], v[92:95], v[182:185], v[4:7]
	v_mfma_f32_16x16x32_bf16 v[182:185], v[92:95], v[196:199], v[0:3]
	s_nop 1
	v_add_u32_e32 v0, 0x18000, v129
	s_barrier
	ds_read_b128 v[24:27], v0
	ds_read_b128 v[28:31], v0 offset:1024
	ds_read_b128 v[186:189], v0 offset:2048
	ds_read_b128 v[196:199], v0 offset:3072
	ds_read_b128 v[0:3], v128 offset:32768
	ds_read_b128 v[4:7], v128 offset:33792
	ds_read_b128 v[8:11], v128 offset:34816
	ds_read_b128 v[12:15], v128 offset:35840
	ds_read_b128 v[16:19], v128 offset:36864
	ds_read_b128 v[20:23], v128 offset:37888
	ds_read_b128 v[208:211], v128 offset:38912
	ds_read_b128 v[212:215], v128 offset:39936
	s_waitcnt vmcnt(2)
	s_barrier
	s_waitcnt lgkmcnt(0)
	s_waitcnt lgkmcnt(0)
	v_mfma_f32_16x16x32_bf16 v[64:67], v[0:3], v[24:27], v[124:127]
	v_mfma_f32_16x16x32_bf16 v[92:95], v[4:7], v[28:31], v[64:67]
	v_mfma_f32_16x16x32_bf16 v[64:67], v[0:3], v[186:189], v[120:123]
	v_mfma_f32_16x16x32_bf16 v[68:71], v[8:11], v[24:27], v[116:119]
	v_mfma_f32_16x16x32_bf16 v[72:75], v[8:11], v[186:189], v[112:115]
	v_mfma_f32_16x16x32_bf16 v[76:79], v[16:19], v[24:27], v[108:111]
	v_mfma_f32_16x16x32_bf16 v[80:83], v[16:19], v[186:189], v[104:107]
	v_mfma_f32_16x16x32_bf16 v[84:87], v[208:211], v[24:27], v[100:103]
	v_mfma_f32_16x16x32_bf16 v[88:91], v[208:211], v[186:189], v[96:99]
	v_mfma_f32_16x16x32_bf16 v[64:67], v[4:7], v[196:199], v[64:67]
	v_mfma_f32_16x16x32_bf16 v[68:71], v[12:15], v[28:31], v[68:71]
	v_mfma_f32_16x16x32_bf16 v[72:75], v[12:15], v[196:199], v[72:75]
	v_mfma_f32_16x16x32_bf16 v[76:79], v[20:23], v[28:31], v[76:79]
	v_mfma_f32_16x16x32_bf16 v[80:83], v[20:23], v[196:199], v[80:83]
	v_mfma_f32_16x16x32_bf16 v[84:87], v[212:215], v[28:31], v[84:87]
	v_mfma_f32_16x16x32_bf16 v[88:91], v[212:215], v[196:199], v[88:91]
	v_add_u32_e32 v96, 0x1c000, v129
	s_barrier
	ds_read_b128 v[216:219], v96
	ds_read_b128 v[220:223], v96 offset:1024
	ds_read_b128 v[224:227], v96 offset:2048
	ds_read_b128 v[228:231], v96 offset:3072
	s_waitcnt vmcnt(0)
	s_barrier
	s_waitcnt lgkmcnt(0)
	s_waitcnt lgkmcnt(0)
	v_mfma_f32_16x16x32_bf16 v[96:99], v[0:3], v[216:219], v[200:203]
	v_mfma_f32_16x16x32_bf16 v[0:3], v[0:3], v[224:227], v[150:153]
	v_mfma_f32_16x16x32_bf16 v[124:127], v[4:7], v[220:223], v[96:99]
	v_mfma_f32_16x16x32_bf16 v[96:99], v[4:7], v[228:231], v[0:3]
	v_mfma_f32_16x16x32_bf16 v[0:3], v[8:11], v[216:219], v[154:157]
	v_mfma_f32_16x16x32_bf16 v[100:103], v[12:15], v[220:223], v[0:3]
	v_mfma_f32_16x16x32_bf16 v[0:3], v[8:11], v[224:227], v[158:161]
	v_mfma_f32_16x16x32_bf16 v[104:107], v[12:15], v[228:231], v[0:3]
	v_mfma_f32_16x16x32_bf16 v[0:3], v[16:19], v[216:219], v[162:165]
	v_mfma_f32_16x16x32_bf16 v[108:111], v[20:23], v[220:223], v[0:3]
	v_mfma_f32_16x16x32_bf16 v[0:3], v[16:19], v[224:227], v[166:169]
	v_mfma_f32_16x16x32_bf16 v[112:115], v[20:23], v[228:231], v[0:3]
	v_mfma_f32_16x16x32_bf16 v[0:3], v[208:211], v[216:219], v[170:173]
	v_mfma_f32_16x16x32_bf16 v[116:119], v[212:215], v[220:223], v[0:3]
	v_mfma_f32_16x16x32_bf16 v[0:3], v[208:211], v[224:227], v[174:177]
	v_mfma_f32_16x16x32_bf16 v[120:123], v[212:215], v[228:231], v[0:3]
	s_barrier
	ds_read_b128 v[150:153], v128 offset:49152
	ds_read_b128 v[154:157], v128 offset:50176
	ds_read_b128 v[158:161], v128 offset:51200
	ds_read_b128 v[162:165], v128 offset:52224
	ds_read_b128 v[166:169], v128 offset:53248
	ds_read_b128 v[170:173], v128 offset:54272
	ds_read_b128 v[174:177], v128 offset:55296
	ds_read_b128 v[200:203], v128 offset:56320
	s_barrier
	s_waitcnt lgkmcnt(0)
	s_waitcnt lgkmcnt(0)
	v_mfma_f32_16x16x32_bf16 v[0:3], v[150:153], v[24:27], v[60:63]
	v_mfma_f32_16x16x32_bf16 v[8:11], v[158:161], v[24:27], v[52:55]
	v_mfma_f32_16x16x32_bf16 v[16:19], v[166:169], v[24:27], v[44:47]
	v_mfma_f32_16x16x32_bf16 v[24:27], v[174:177], v[24:27], v[36:39]
	v_mfma_f32_16x16x32_bf16 v[0:3], v[154:157], v[28:31], v[0:3]
	v_mfma_f32_16x16x32_bf16 v[4:7], v[150:153], v[186:189], v[56:59]
	v_mfma_f32_16x16x32_bf16 v[8:11], v[162:165], v[28:31], v[8:11]
	v_mfma_f32_16x16x32_bf16 v[12:15], v[158:161], v[186:189], v[48:51]
	v_mfma_f32_16x16x32_bf16 v[16:19], v[170:173], v[28:31], v[16:19]
	v_mfma_f32_16x16x32_bf16 v[20:23], v[166:169], v[186:189], v[40:43]
	v_mfma_f32_16x16x32_bf16 v[24:27], v[200:203], v[28:31], v[24:27]
	v_mfma_f32_16x16x32_bf16 v[28:31], v[174:177], v[186:189], v[32:35]
	v_mfma_f32_16x16x32_bf16 v[4:7], v[154:157], v[196:199], v[4:7]
	v_mfma_f32_16x16x32_bf16 v[12:15], v[162:165], v[196:199], v[12:15]
	v_mfma_f32_16x16x32_bf16 v[20:23], v[170:173], v[196:199], v[20:23]
	v_mfma_f32_16x16x32_bf16 v[28:31], v[200:203], v[196:199], v[28:31]
	v_mfma_f32_16x16x32_bf16 v[32:35], v[150:153], v[216:219], v[130:133]
	v_mfma_f32_16x16x32_bf16 v[36:39], v[150:153], v[224:227], v[134:137]
	v_mfma_f32_16x16x32_bf16 v[40:43], v[158:161], v[216:219], v[138:141]
	v_mfma_f32_16x16x32_bf16 v[44:47], v[158:161], v[224:227], v[146:149]
	v_mfma_f32_16x16x32_bf16 v[48:51], v[166:169], v[216:219], v[178:181]
	v_mfma_f32_16x16x32_bf16 v[52:55], v[166:169], v[224:227], v[204:207]
	v_mfma_f32_16x16x32_bf16 v[56:59], v[174:177], v[216:219], v[142:145]
	v_mfma_f32_16x16x32_bf16 v[60:63], v[174:177], v[224:227], v[182:185]
	v_mfma_f32_16x16x32_bf16 v[32:35], v[154:157], v[220:223], v[32:35]
	v_mfma_f32_16x16x32_bf16 v[36:39], v[154:157], v[228:231], v[36:39]
	v_mfma_f32_16x16x32_bf16 v[40:43], v[162:165], v[220:223], v[40:43]
	v_mfma_f32_16x16x32_bf16 v[44:47], v[162:165], v[228:231], v[44:47]
	v_mfma_f32_16x16x32_bf16 v[48:51], v[170:173], v[220:223], v[48:51]
	v_mfma_f32_16x16x32_bf16 v[52:55], v[170:173], v[228:231], v[52:55]
	v_mfma_f32_16x16x32_bf16 v[56:59], v[200:203], v[220:223], v[56:59]
	v_mfma_f32_16x16x32_bf16 v[60:63], v[200:203], v[228:231], v[60:63]
	s_cmpk_gt_u32 s47, 0xff
	s_barrier
	s_cbranch_scc1 .LBB0_365
	s_barrier

.LBB0_830:
	v_add_u32_e32 v143, s77, v136
	ds_read_b128 v[150:153], v143
	ds_read_b128 v[154:157], v143 offset:1024
	ds_read_b128 v[158:161], v143 offset:2048
	ds_read_b128 v[162:165], v143 offset:3072
	s_add_u32 s53, s12, s38
	s_addc_u32 s72, s13, s39
	s_add_u32 s54, s53, 0x80
	s_addc_u32 s55, s72, 0
	v_add_u32_e32 v143, 0xc000, v130
	v_lshl_add_u64 v[144:145], s[54:55], 0, v[192:193]
	v_readfirstlane_b32 s54, v143
	s_mov_b32 m0, s54
	ds_read_b128 v[166:169], v148
	ds_read_b128 v[170:173], v148 offset:1024
	ds_read_b128 v[174:177], v148 offset:2048
	ds_read_b128 v[178:181], v148 offset:3072
	ds_read_b128 v[182:185], v148 offset:4096
	ds_read_b128 v[186:189], v148 offset:5120
	ds_read_b128 v[196:199], v148 offset:6144
	ds_read_b128 v[200:203], v148 offset:7168
	global_load_lds_dwordx4 v[144:145], off
	v_lshl_add_u64 v[146:147], v[144:145], 0, s[6:7]
	v_add_u32_e32 v144, 0xe000, v130
	s_nop 0
	v_readfirstlane_b32 s54, v144
	s_mov_b32 m0, s54
	s_nop 0
	global_load_lds_dwordx4 v[146:147], off
	s_waitcnt lgkmcnt(8)
	s_barrier
	s_waitcnt lgkmcnt(0)
	s_waitcnt lgkmcnt(0)
	v_mfma_f32_16x16x32_bf16 v[124:127], v[166:169], v[150:153], v[124:127]
	v_mfma_f32_16x16x32_bf16 v[120:123], v[166:169], v[158:161], v[120:123]
	v_mfma_f32_16x16x32_bf16 v[116:119], v[174:177], v[150:153], v[116:119]
	v_mfma_f32_16x16x32_bf16 v[112:115], v[174:177], v[158:161], v[112:115]
	v_mfma_f32_16x16x32_bf16 v[108:111], v[182:185], v[150:153], v[108:111]
	v_mfma_f32_16x16x32_bf16 v[104:107], v[182:185], v[158:161], v[104:107]
	v_mfma_f32_16x16x32_bf16 v[100:103], v[196:199], v[150:153], v[100:103]
	v_mfma_f32_16x16x32_bf16 v[96:99], v[196:199], v[158:161], v[96:99]
	v_mfma_f32_16x16x32_bf16 v[124:127], v[170:173], v[154:157], v[124:127]
	v_mfma_f32_16x16x32_bf16 v[120:123], v[170:173], v[162:165], v[120:123]
	v_mfma_f32_16x16x32_bf16 v[116:119], v[178:181], v[154:157], v[116:119]
	v_mfma_f32_16x16x32_bf16 v[112:115], v[178:181], v[162:165], v[112:115]
	v_mfma_f32_16x16x32_bf16 v[108:111], v[186:189], v[154:157], v[108:111]
	v_mfma_f32_16x16x32_bf16 v[104:107], v[186:189], v[162:165], v[104:107]
	v_mfma_f32_16x16x32_bf16 v[100:103], v[200:203], v[154:157], v[100:103]
	v_mfma_f32_16x16x32_bf16 v[96:99], v[200:203], v[162:165], v[96:99]
	s_barrier
	s_add_u32 s73, s0, s38
	s_addc_u32 s74, s1, s39
	s_add_u32 s54, s73, 0x100
	s_addc_u32 s55, s74, 0
	v_lshl_add_u64 v[146:147], s[54:55], 0, v[192:193]
	v_readfirstlane_b32 s54, v128
	v_add_u32_e32 v145, s33, v136
	s_mov_b32 m0, s54
	v_readfirstlane_b32 s54, v129
	ds_read_b128 v[204:207], v145
	ds_read_b128 v[208:211], v145 offset:1024
	ds_read_b128 v[212:215], v145 offset:2048
	ds_read_b128 v[216:219], v145 offset:3072
	global_load_lds_dwordx4 v[146:147], off
	v_lshl_add_u64 v[146:147], v[146:147], 0, s[6:7]
	s_mov_b32 m0, s54
	s_nop 0
	global_load_lds_dwordx4 v[146:147], off
	s_barrier
	s_waitcnt lgkmcnt(0)
	s_waitcnt lgkmcnt(0)
	v_mfma_f32_16x16x32_bf16 v[92:95], v[166:169], v[204:207], v[92:95]
	v_mfma_f32_16x16x32_bf16 v[88:91], v[166:169], v[212:215], v[88:91]
	v_mfma_f32_16x16x32_bf16 v[84:87], v[174:177], v[204:207], v[84:87]
	v_mfma_f32_16x16x32_bf16 v[80:83], v[174:177], v[212:215], v[80:83]
	v_mfma_f32_16x16x32_bf16 v[76:79], v[182:185], v[204:207], v[76:79]
	v_mfma_f32_16x16x32_bf16 v[72:75], v[182:185], v[212:215], v[72:75]
	v_mfma_f32_16x16x32_bf16 v[68:71], v[196:199], v[204:207], v[68:71]
	v_mfma_f32_16x16x32_bf16 v[64:67], v[196:199], v[212:215], v[64:67]
	v_mfma_f32_16x16x32_bf16 v[92:95], v[170:173], v[208:211], v[92:95]
	v_mfma_f32_16x16x32_bf16 v[88:91], v[170:173], v[216:219], v[88:91]
	v_mfma_f32_16x16x32_bf16 v[84:87], v[178:181], v[208:211], v[84:87]
	v_mfma_f32_16x16x32_bf16 v[80:83], v[178:181], v[216:219], v[80:83]
	v_mfma_f32_16x16x32_bf16 v[76:79], v[186:189], v[208:211], v[76:79]
	v_mfma_f32_16x16x32_bf16 v[72:75], v[186:189], v[216:219], v[72:75]
	v_mfma_f32_16x16x32_bf16 v[68:71], v[200:203], v[208:211], v[68:71]
	v_mfma_f32_16x16x32_bf16 v[64:67], v[200:203], v[216:219], v[64:67]
	s_add_u32 s75, s2, s38
	s_addc_u32 s78, s3, s39
	s_add_u32 s54, s75, 0x100
	s_addc_u32 s55, s78, 0
	v_lshl_add_u64 v[146:147], s[54:55], 0, v[192:193]
	v_readfirstlane_b32 s54, v130
	s_mov_b32 m0, s54
	v_readfirstlane_b32 s54, v131
	s_barrier
	ds_read_b128 v[166:169], v148 offset:16384
	ds_read_b128 v[170:173], v148 offset:17408
	ds_read_b128 v[174:177], v148 offset:18432
	ds_read_b128 v[178:181], v148 offset:19456
	ds_read_b128 v[182:185], v148 offset:20480
	ds_read_b128 v[186:189], v148 offset:21504
	ds_read_b128 v[196:199], v148 offset:22528
	ds_read_b128 v[200:203], v148 offset:23552
	global_load_lds_dwordx4 v[146:147], off
	v_lshl_add_u64 v[146:147], v[146:147], 0, s[6:7]
	s_mov_b32 m0, s54
	s_nop 0
	global_load_lds_dwordx4 v[146:147], off
	s_barrier
	s_waitcnt lgkmcnt(0)
	s_waitcnt lgkmcnt(0)
	v_mfma_f32_16x16x32_bf16 v[60:63], v[166:169], v[150:153], v[60:63]
	v_mfma_f32_16x16x32_bf16 v[56:59], v[166:169], v[158:161], v[56:59]
	v_mfma_f32_16x16x32_bf16 v[52:55], v[174:177], v[150:153], v[52:55]
	v_mfma_f32_16x16x32_bf16 v[48:51], v[174:177], v[158:161], v[48:51]
	v_mfma_f32_16x16x32_bf16 v[44:47], v[182:185], v[150:153], v[44:47]
	v_mfma_f32_16x16x32_bf16 v[40:43], v[182:185], v[158:161], v[40:43]
	v_mfma_f32_16x16x32_bf16 v[36:39], v[196:199], v[150:153], v[36:39]
	v_mfma_f32_16x16x32_bf16 v[32:35], v[196:199], v[158:161], v[32:35]
	v_mfma_f32_16x16x32_bf16 v[60:63], v[170:173], v[154:157], v[60:63]
	v_mfma_f32_16x16x32_bf16 v[56:59], v[170:173], v[162:165], v[56:59]
	v_mfma_f32_16x16x32_bf16 v[52:55], v[178:181], v[154:157], v[52:55]
	v_mfma_f32_16x16x32_bf16 v[48:51], v[178:181], v[162:165], v[48:51]
	v_mfma_f32_16x16x32_bf16 v[44:47], v[186:189], v[154:157], v[44:47]
	v_mfma_f32_16x16x32_bf16 v[40:43], v[186:189], v[162:165], v[40:43]
	v_mfma_f32_16x16x32_bf16 v[36:39], v[200:203], v[154:157], v[36:39]
	v_mfma_f32_16x16x32_bf16 v[32:35], v[200:203], v[162:165], v[32:35]
	s_barrier
	s_add_u32 s79, s36, s38
	s_addc_u32 s80, s37, s39
	s_add_u32 s54, s79, 0x100
	s_addc_u32 s55, s80, 0
	v_lshl_add_u64 v[146:147], s[54:55], 0, v[192:193]
	v_readfirstlane_b32 s54, v132
	s_mov_b32 m0, s54
	v_readfirstlane_b32 s54, v133
	global_load_lds_dwordx4 v[146:147], off
	v_lshl_add_u64 v[146:147], v[146:147], 0, s[6:7]
	s_mov_b32 m0, s54
	s_nop 0
	global_load_lds_dwordx4 v[146:147], off
	s_waitcnt vmcnt(6)
	s_barrier
	v_mfma_f32_16x16x32_bf16 v[28:31], v[166:169], v[204:207], v[28:31]
	v_mfma_f32_16x16x32_bf16 v[24:27], v[166:169], v[212:215], v[24:27]
	v_mfma_f32_16x16x32_bf16 v[20:23], v[174:177], v[204:207], v[20:23]
	v_mfma_f32_16x16x32_bf16 v[16:19], v[174:177], v[212:215], v[16:19]
	v_mfma_f32_16x16x32_bf16 v[12:15], v[182:185], v[204:207], v[12:15]
	v_mfma_f32_16x16x32_bf16 v[8:11], v[182:185], v[212:215], v[8:11]
	v_mfma_f32_16x16x32_bf16 v[4:7], v[196:199], v[204:207], v[4:7]
	v_mfma_f32_16x16x32_bf16 v[0:3], v[196:199], v[212:215], v[0:3]
	v_mfma_f32_16x16x32_bf16 v[28:31], v[170:173], v[208:211], v[28:31]
	v_mfma_f32_16x16x32_bf16 v[24:27], v[170:173], v[216:219], v[24:27]
	v_mfma_f32_16x16x32_bf16 v[20:23], v[178:181], v[208:211], v[20:23]
	v_mfma_f32_16x16x32_bf16 v[16:19], v[178:181], v[216:219], v[16:19]
	v_mfma_f32_16x16x32_bf16 v[12:15], v[186:189], v[208:211], v[12:15]
	v_mfma_f32_16x16x32_bf16 v[8:11], v[186:189], v[216:219], v[8:11]
	v_mfma_f32_16x16x32_bf16 v[4:7], v[200:203], v[208:211], v[4:7]
	v_mfma_f32_16x16x32_bf16 v[0:3], v[200:203], v[216:219], v[0:3]
	v_add_u32_e32 v145, s93, v136
	s_barrier
	ds_read_b128 v[150:153], v145
	ds_read_b128 v[154:157], v145 offset:1024
	ds_read_b128 v[158:161], v145 offset:2048
	ds_read_b128 v[162:165], v145 offset:3072
	s_add_u32 s54, s53, 0x100
	s_addc_u32 s55, s72, 0
	v_readfirstlane_b32 s53, v134
	v_lshl_add_u64 v[146:147], s[54:55], 0, v[192:193]
	s_mov_b32 m0, s53
	v_readfirstlane_b32 s53, v135
	ds_read_b128 v[166:169], v148 offset:32768
	ds_read_b128 v[170:173], v148 offset:33792
	ds_read_b128 v[174:177], v148 offset:34816
	ds_read_b128 v[178:181], v148 offset:35840
	ds_read_b128 v[182:185], v148 offset:36864
	ds_read_b128 v[186:189], v148 offset:37888
	ds_read_b128 v[196:199], v148 offset:38912
	ds_read_b128 v[200:203], v148 offset:39936
	global_load_lds_dwordx4 v[146:147], off
	v_lshl_add_u64 v[146:147], v[146:147], 0, s[6:7]
	s_mov_b32 m0, s53
	s_nop 0
	global_load_lds_dwordx4 v[146:147], off
	s_waitcnt lgkmcnt(8)
	s_barrier
	s_waitcnt lgkmcnt(0)
	s_waitcnt lgkmcnt(0)
	v_mfma_f32_16x16x32_bf16 v[124:127], v[166:169], v[150:153], v[124:127]
	v_mfma_f32_16x16x32_bf16 v[120:123], v[166:169], v[158:161], v[120:123]
	v_mfma_f32_16x16x32_bf16 v[116:119], v[174:177], v[150:153], v[116:119]
	v_mfma_f32_16x16x32_bf16 v[112:115], v[174:177], v[158:161], v[112:115]
	v_mfma_f32_16x16x32_bf16 v[108:111], v[182:185], v[150:153], v[108:111]
	v_mfma_f32_16x16x32_bf16 v[104:107], v[182:185], v[158:161], v[104:107]
	v_mfma_f32_16x16x32_bf16 v[100:103], v[196:199], v[150:153], v[100:103]
	v_mfma_f32_16x16x32_bf16 v[96:99], v[196:199], v[158:161], v[96:99]
	v_mfma_f32_16x16x32_bf16 v[124:127], v[170:173], v[154:157], v[124:127]
	v_mfma_f32_16x16x32_bf16 v[120:123], v[170:173], v[162:165], v[120:123]
	v_mfma_f32_16x16x32_bf16 v[116:119], v[178:181], v[154:157], v[116:119]
	v_mfma_f32_16x16x32_bf16 v[112:115], v[178:181], v[162:165], v[112:115]
	v_mfma_f32_16x16x32_bf16 v[108:111], v[186:189], v[154:157], v[108:111]
	v_mfma_f32_16x16x32_bf16 v[104:107], v[186:189], v[162:165], v[104:107]
	v_mfma_f32_16x16x32_bf16 v[100:103], v[200:203], v[154:157], v[100:103]
	v_mfma_f32_16x16x32_bf16 v[96:99], v[200:203], v[162:165], v[96:99]
	s_barrier
	s_add_u32 s54, s73, 0x180
	s_addc_u32 s55, s74, 0
	v_readfirstlane_b32 s53, v137
	v_add_u32_e32 v145, s89, v136
	v_lshl_add_u64 v[146:147], s[54:55], 0, v[192:193]
	s_mov_b32 m0, s53
	v_readfirstlane_b32 s53, v138
	ds_read_b128 v[204:207], v145
	ds_read_b128 v[208:211], v145 offset:1024
	ds_read_b128 v[212:215], v145 offset:2048
	ds_read_b128 v[216:219], v145 offset:3072
	global_load_lds_dwordx4 v[146:147], off
	v_lshl_add_u64 v[146:147], v[146:147], 0, s[6:7]
	s_mov_b32 m0, s53
	s_nop 0
	global_load_lds_dwordx4 v[146:147], off
	s_barrier
	s_waitcnt lgkmcnt(0)
	s_waitcnt lgkmcnt(0)
	v_mfma_f32_16x16x32_bf16 v[92:95], v[166:169], v[204:207], v[92:95]
	v_mfma_f32_16x16x32_bf16 v[88:91], v[166:169], v[212:215], v[88:91]
	v_mfma_f32_16x16x32_bf16 v[84:87], v[174:177], v[204:207], v[84:87]
	v_mfma_f32_16x16x32_bf16 v[80:83], v[174:177], v[212:215], v[80:83]
	v_mfma_f32_16x16x32_bf16 v[76:79], v[182:185], v[204:207], v[76:79]
	v_mfma_f32_16x16x32_bf16 v[72:75], v[182:185], v[212:215], v[72:75]
	v_mfma_f32_16x16x32_bf16 v[68:71], v[196:199], v[204:207], v[68:71]
	v_mfma_f32_16x16x32_bf16 v[64:67], v[196:199], v[212:215], v[64:67]
	v_mfma_f32_16x16x32_bf16 v[92:95], v[170:173], v[208:211], v[92:95]
	v_mfma_f32_16x16x32_bf16 v[88:91], v[170:173], v[216:219], v[88:91]
	v_mfma_f32_16x16x32_bf16 v[84:87], v[178:181], v[208:211], v[84:87]
	v_mfma_f32_16x16x32_bf16 v[80:83], v[178:181], v[216:219], v[80:83]
	v_mfma_f32_16x16x32_bf16 v[76:79], v[186:189], v[208:211], v[76:79]
	v_mfma_f32_16x16x32_bf16 v[72:75], v[186:189], v[216:219], v[72:75]
	v_mfma_f32_16x16x32_bf16 v[68:71], v[200:203], v[208:211], v[68:71]
	v_mfma_f32_16x16x32_bf16 v[64:67], v[200:203], v[216:219], v[64:67]
	s_add_u32 s54, s75, 0x180
	s_addc_u32 s55, s78, 0
	v_readfirstlane_b32 s53, v139
	v_lshl_add_u64 v[146:147], s[54:55], 0, v[192:193]
	s_mov_b32 m0, s53
	v_readfirstlane_b32 s53, v140
	s_barrier
	ds_read_b128 v[166:169], v148 offset:49152
	ds_read_b128 v[170:173], v148 offset:50176
	ds_read_b128 v[174:177], v148 offset:51200
	ds_read_b128 v[178:181], v148 offset:52224
	ds_read_b128 v[182:185], v148 offset:53248
	ds_read_b128 v[186:189], v148 offset:54272
	ds_read_b128 v[196:199], v148 offset:55296
	ds_read_b128 v[200:203], v148 offset:56320
	global_load_lds_dwordx4 v[146:147], off
	v_lshl_add_u64 v[146:147], v[146:147], 0, s[6:7]
	s_mov_b32 m0, s53
	s_nop 0
	global_load_lds_dwordx4 v[146:147], off
	s_barrier
	s_waitcnt lgkmcnt(0)
	s_waitcnt lgkmcnt(0)
	v_mfma_f32_16x16x32_bf16 v[60:63], v[166:169], v[150:153], v[60:63]
	v_mfma_f32_16x16x32_bf16 v[56:59], v[166:169], v[158:161], v[56:59]
	v_mfma_f32_16x16x32_bf16 v[52:55], v[174:177], v[150:153], v[52:55]
	v_mfma_f32_16x16x32_bf16 v[48:51], v[174:177], v[158:161], v[48:51]
	v_mfma_f32_16x16x32_bf16 v[44:47], v[182:185], v[150:153], v[44:47]
	v_mfma_f32_16x16x32_bf16 v[40:43], v[182:185], v[158:161], v[40:43]
	v_mfma_f32_16x16x32_bf16 v[36:39], v[196:199], v[150:153], v[36:39]
	v_mfma_f32_16x16x32_bf16 v[32:35], v[196:199], v[158:161], v[32:35]
	v_mfma_f32_16x16x32_bf16 v[60:63], v[170:173], v[154:157], v[60:63]
	v_mfma_f32_16x16x32_bf16 v[56:59], v[170:173], v[162:165], v[56:59]
	v_mfma_f32_16x16x32_bf16 v[52:55], v[178:181], v[154:157], v[52:55]
	v_mfma_f32_16x16x32_bf16 v[48:51], v[178:181], v[162:165], v[48:51]
	v_mfma_f32_16x16x32_bf16 v[44:47], v[186:189], v[154:157], v[44:47]
	v_mfma_f32_16x16x32_bf16 v[40:43], v[186:189], v[162:165], v[40:43]
	v_mfma_f32_16x16x32_bf16 v[36:39], v[200:203], v[154:157], v[36:39]
	v_mfma_f32_16x16x32_bf16 v[32:35], v[200:203], v[162:165], v[32:35]
	s_barrier
	s_add_u32 s54, s79, 0x180
	s_addc_u32 s55, s80, 0
	v_readfirstlane_b32 s53, v141
	v_lshl_add_u64 v[146:147], s[54:55], 0, v[192:193]
	s_mov_b32 m0, s53
	v_readfirstlane_b32 s53, v142
	global_load_lds_dwordx4 v[146:147], off
	v_lshl_add_u64 v[146:147], v[146:147], 0, s[6:7]
	s_mov_b32 m0, s53
	s_nop 0
	global_load_lds_dwordx4 v[146:147], off
	s_waitcnt vmcnt(6)
	s_barrier
	v_mfma_f32_16x16x32_bf16 v[28:31], v[166:169], v[204:207], v[28:31]
	v_mfma_f32_16x16x32_bf16 v[24:27], v[166:169], v[212:215], v[24:27]
	v_mfma_f32_16x16x32_bf16 v[20:23], v[174:177], v[204:207], v[20:23]
	v_mfma_f32_16x16x32_bf16 v[16:19], v[174:177], v[212:215], v[16:19]
	v_mfma_f32_16x16x32_bf16 v[12:15], v[182:185], v[204:207], v[12:15]
	v_mfma_f32_16x16x32_bf16 v[8:11], v[182:185], v[212:215], v[8:11]
	v_mfma_f32_16x16x32_bf16 v[4:7], v[196:199], v[204:207], v[4:7]
	v_mfma_f32_16x16x32_bf16 v[0:3], v[196:199], v[212:215], v[0:3]
	v_mfma_f32_16x16x32_bf16 v[28:31], v[170:173], v[208:211], v[28:31]
	v_mfma_f32_16x16x32_bf16 v[24:27], v[170:173], v[216:219], v[24:27]
	v_mfma_f32_16x16x32_bf16 v[20:23], v[178:181], v[208:211], v[20:23]
	v_mfma_f32_16x16x32_bf16 v[16:19], v[178:181], v[216:219], v[16:19]
	v_mfma_f32_16x16x32_bf16 v[12:15], v[186:189], v[208:211], v[12:15]
	v_mfma_f32_16x16x32_bf16 v[8:11], v[186:189], v[216:219], v[8:11]
	v_mfma_f32_16x16x32_bf16 v[4:7], v[200:203], v[208:211], v[4:7]
	v_mfma_f32_16x16x32_bf16 v[0:3], v[200:203], v[216:219], v[0:3]
	s_add_i32 s52, s52, 2
	s_add_u32 s38, s38, 0x100
	s_addc_u32 s39, s39, 0
	s_cmp_lt_u32 s52, 4
	s_barrier
	s_cbranch_scc1 .LBB0_830
	v_add_u32_e32 v149, 0, v136
	s_add_u32 s0, s12, 0x380
	v_add_u32_e32 v140, 0x10000, v149
	s_addc_u32 s1, s13, 0
	ds_read_b128 v[128:131], v140
	ds_read_b128 v[132:135], v140 offset:1024
	ds_read_b128 v[136:139], v140 offset:2048
	ds_read_b128 v[150:153], v140 offset:3072
	ds_read_b128 v[154:157], v148
	ds_read_b128 v[158:161], v148 offset:1024
	ds_read_b128 v[162:165], v148 offset:2048
	ds_read_b128 v[166:169], v148 offset:3072
	ds_read_b128 v[170:173], v148 offset:4096
	ds_read_b128 v[174:177], v148 offset:5120
	ds_read_b128 v[178:181], v148 offset:6144
	ds_read_b128 v[182:185], v148 offset:7168
	v_lshl_add_u64 v[140:141], s[0:1], 0, v[192:193]
	v_readfirstlane_b32 s0, v143
	s_mov_b32 m0, s0
	v_readfirstlane_b32 s0, v144
	global_load_lds_dwordx4 v[140:141], off
	v_lshl_add_u64 v[140:141], v[140:141], 0, s[6:7]
	s_mov_b32 m0, s0
	s_nop 0
	global_load_lds_dwordx4 v[140:141], off
	s_barrier
	s_waitcnt lgkmcnt(0)
	s_waitcnt lgkmcnt(0)
	v_mfma_f32_16x16x32_bf16 v[124:127], v[154:157], v[128:131], v[124:127]
	v_mfma_f32_16x16x32_bf16 v[120:123], v[154:157], v[136:139], v[120:123]
	v_mfma_f32_16x16x32_bf16 v[116:119], v[162:165], v[128:131], v[116:119]
	v_mfma_f32_16x16x32_bf16 v[112:115], v[162:165], v[136:139], v[112:115]
	v_mfma_f32_16x16x32_bf16 v[108:111], v[170:173], v[128:131], v[108:111]
	v_mfma_f32_16x16x32_bf16 v[104:107], v[170:173], v[136:139], v[104:107]
	v_mfma_f32_16x16x32_bf16 v[100:103], v[178:181], v[128:131], v[100:103]
	v_mfma_f32_16x16x32_bf16 v[124:127], v[158:161], v[132:135], v[124:127]
	v_mfma_f32_16x16x32_bf16 v[120:123], v[158:161], v[150:153], v[120:123]
	v_mfma_f32_16x16x32_bf16 v[140:143], v[166:169], v[132:135], v[116:119]
	v_mfma_f32_16x16x32_bf16 v[112:115], v[166:169], v[150:153], v[112:115]
	v_mfma_f32_16x16x32_bf16 v[108:111], v[174:177], v[132:135], v[108:111]
	v_mfma_f32_16x16x32_bf16 v[104:107], v[174:177], v[150:153], v[104:107]
	v_mfma_f32_16x16x32_bf16 v[144:147], v[182:185], v[132:135], v[100:103]
	v_mfma_f32_16x16x32_bf16 v[96:99], v[178:181], v[136:139], v[96:99]
	v_mfma_f32_16x16x32_bf16 v[186:189], v[182:185], v[150:153], v[96:99]
	v_add_u32_e32 v190, 0x14000, v149
	s_barrier
	s_nop 3
	ds_read_b128 v[96:99], v190
	ds_read_b128 v[100:103], v190 offset:1024
	ds_read_b128 v[116:119], v190 offset:2048
	ds_read_b128 v[196:199], v190 offset:3072
	s_barrier
	s_waitcnt lgkmcnt(0)
	s_waitcnt lgkmcnt(0)
	v_mfma_f32_16x16x32_bf16 v[92:95], v[154:157], v[96:99], v[92:95]
	v_mfma_f32_16x16x32_bf16 v[88:91], v[154:157], v[116:119], v[88:91]
	v_mfma_f32_16x16x32_bf16 v[84:87], v[162:165], v[96:99], v[84:87]
	v_mfma_f32_16x16x32_bf16 v[80:83], v[162:165], v[116:119], v[80:83]
	v_mfma_f32_16x16x32_bf16 v[76:79], v[170:173], v[96:99], v[76:79]
	v_mfma_f32_16x16x32_bf16 v[72:75], v[170:173], v[116:119], v[72:75]
	v_mfma_f32_16x16x32_bf16 v[68:71], v[178:181], v[96:99], v[68:71]
	v_mfma_f32_16x16x32_bf16 v[64:67], v[178:181], v[116:119], v[64:67]
	v_mfma_f32_16x16x32_bf16 v[200:203], v[158:161], v[100:103], v[92:95]
	v_mfma_f32_16x16x32_bf16 v[156:159], v[158:161], v[196:199], v[88:91]
	v_mfma_f32_16x16x32_bf16 v[84:87], v[166:169], v[100:103], v[84:87]
	v_mfma_f32_16x16x32_bf16 v[80:83], v[166:169], v[196:199], v[80:83]
	v_mfma_f32_16x16x32_bf16 v[76:79], v[174:177], v[100:103], v[76:79]
	v_mfma_f32_16x16x32_bf16 v[72:75], v[174:177], v[196:199], v[72:75]
	v_mfma_f32_16x16x32_bf16 v[68:71], v[182:185], v[100:103], v[68:71]
	v_mfma_f32_16x16x32_bf16 v[64:67], v[182:185], v[196:199], v[64:67]
	s_barrier
	ds_read_b128 v[88:91], v148 offset:16384
	ds_read_b128 v[92:95], v148 offset:17408
	ds_read_b128 v[160:163], v148 offset:18432
	ds_read_b128 v[164:167], v148 offset:19456
	ds_read_b128 v[168:171], v148 offset:20480
	ds_read_b128 v[172:175], v148 offset:21504
	ds_read_b128 v[176:179], v148 offset:22528
	ds_read_b128 v[180:183], v148 offset:23552
	s_waitcnt vmcnt(4)
	s_barrier
	s_waitcnt lgkmcnt(0)
	s_waitcnt lgkmcnt(0)
	v_mfma_f32_16x16x32_bf16 v[60:63], v[88:91], v[128:131], v[60:63]
	v_mfma_f32_16x16x32_bf16 v[56:59], v[88:91], v[136:139], v[56:59]
	v_mfma_f32_16x16x32_bf16 v[52:55], v[160:163], v[128:131], v[52:55]
	v_mfma_f32_16x16x32_bf16 v[48:51], v[160:163], v[136:139], v[48:51]
	v_mfma_f32_16x16x32_bf16 v[44:47], v[168:171], v[128:131], v[44:47]
	v_mfma_f32_16x16x32_bf16 v[40:43], v[168:171], v[136:139], v[40:43]
	v_mfma_f32_16x16x32_bf16 v[36:39], v[176:179], v[128:131], v[36:39]
	v_mfma_f32_16x16x32_bf16 v[32:35], v[176:179], v[136:139], v[32:35]
	v_mfma_f32_16x16x32_bf16 v[60:63], v[92:95], v[132:135], v[60:63]
	v_mfma_f32_16x16x32_bf16 v[56:59], v[92:95], v[150:153], v[56:59]
	v_mfma_f32_16x16x32_bf16 v[52:55], v[164:167], v[132:135], v[52:55]
	v_mfma_f32_16x16x32_bf16 v[48:51], v[164:167], v[150:153], v[48:51]
	v_mfma_f32_16x16x32_bf16 v[44:47], v[172:175], v[132:135], v[44:47]
	v_mfma_f32_16x16x32_bf16 v[40:43], v[172:175], v[150:153], v[40:43]
	v_mfma_f32_16x16x32_bf16 v[36:39], v[180:183], v[132:135], v[36:39]
	v_mfma_f32_16x16x32_bf16 v[32:35], v[180:183], v[150:153], v[32:35]
	v_mfma_f32_16x16x32_bf16 v[28:31], v[88:91], v[96:99], v[28:31]
	v_mfma_f32_16x16x32_bf16 v[24:27], v[88:91], v[116:119], v[24:27]
	v_mfma_f32_16x16x32_bf16 v[20:23], v[160:163], v[96:99], v[20:23]
	v_mfma_f32_16x16x32_bf16 v[16:19], v[160:163], v[116:119], v[16:19]
	v_mfma_f32_16x16x32_bf16 v[12:15], v[168:171], v[96:99], v[12:15]
	v_mfma_f32_16x16x32_bf16 v[8:11], v[168:171], v[116:119], v[8:11]
	v_mfma_f32_16x16x32_bf16 v[4:7], v[176:179], v[96:99], v[4:7]
	v_mfma_f32_16x16x32_bf16 v[0:3], v[176:179], v[116:119], v[0:3]
	v_mfma_f32_16x16x32_bf16 v[204:207], v[92:95], v[100:103], v[28:31]
	v_mfma_f32_16x16x32_bf16 v[208:211], v[92:95], v[196:199], v[24:27]
	v_mfma_f32_16x16x32_bf16 v[212:215], v[164:167], v[100:103], v[20:23]
	v_mfma_f32_16x16x32_bf16 v[160:163], v[164:167], v[196:199], v[16:19]
	v_mfma_f32_16x16x32_bf16 v[164:167], v[172:175], v[100:103], v[12:15]
	v_mfma_f32_16x16x32_bf16 v[168:171], v[172:175], v[196:199], v[8:11]
	v_mfma_f32_16x16x32_bf16 v[172:175], v[180:183], v[100:103], v[4:7]
	v_mfma_f32_16x16x32_bf16 v[176:179], v[180:183], v[196:199], v[0:3]
	s_nop 1
	v_add_u32_e32 v0, 0x18000, v149
	s_barrier
	ds_read_b128 v[24:27], v0
	ds_read_b128 v[28:31], v0 offset:1024
	ds_read_b128 v[180:183], v0 offset:2048
	ds_read_b128 v[196:199], v0 offset:3072
	ds_read_b128 v[0:3], v148 offset:32768
	ds_read_b128 v[4:7], v148 offset:33792
	ds_read_b128 v[8:11], v148 offset:34816
	ds_read_b128 v[12:15], v148 offset:35840
	ds_read_b128 v[16:19], v148 offset:36864
	ds_read_b128 v[20:23], v148 offset:37888
	ds_read_b128 v[216:219], v148 offset:38912
	ds_read_b128 v[220:223], v148 offset:39936
	s_waitcnt vmcnt(2)
	s_barrier
	s_waitcnt lgkmcnt(0)
	s_waitcnt lgkmcnt(0)
	v_mfma_f32_16x16x32_bf16 v[88:91], v[0:3], v[24:27], v[124:127]
	v_mfma_f32_16x16x32_bf16 v[116:119], v[4:7], v[28:31], v[88:91]
	v_mfma_f32_16x16x32_bf16 v[88:91], v[0:3], v[180:183], v[120:123]
	v_mfma_f32_16x16x32_bf16 v[92:95], v[8:11], v[24:27], v[140:143]
	v_mfma_f32_16x16x32_bf16 v[96:99], v[8:11], v[180:183], v[112:115]
	v_mfma_f32_16x16x32_bf16 v[100:103], v[16:19], v[24:27], v[108:111]
	v_mfma_f32_16x16x32_bf16 v[104:107], v[16:19], v[180:183], v[104:107]
	v_mfma_f32_16x16x32_bf16 v[108:111], v[216:219], v[24:27], v[144:147]
	v_mfma_f32_16x16x32_bf16 v[112:115], v[216:219], v[180:183], v[186:189]
	v_mfma_f32_16x16x32_bf16 v[88:91], v[4:7], v[196:199], v[88:91]
	v_mfma_f32_16x16x32_bf16 v[92:95], v[12:15], v[28:31], v[92:95]
	v_mfma_f32_16x16x32_bf16 v[96:99], v[12:15], v[196:199], v[96:99]
	v_mfma_f32_16x16x32_bf16 v[100:103], v[20:23], v[28:31], v[100:103]
	v_mfma_f32_16x16x32_bf16 v[104:107], v[20:23], v[196:199], v[104:107]
	v_mfma_f32_16x16x32_bf16 v[108:111], v[220:223], v[28:31], v[108:111]
	v_mfma_f32_16x16x32_bf16 v[112:115], v[220:223], v[196:199], v[112:115]
	v_add_u32_e32 v120, 0x1c000, v149
	s_barrier
	ds_read_b128 v[184:187], v120
	ds_read_b128 v[188:191], v120 offset:1024
	ds_read_b128 v[224:227], v120 offset:2048
	ds_read_b128 v[228:231], v120 offset:3072
	s_waitcnt vmcnt(0)
	s_barrier
	s_waitcnt lgkmcnt(0)
	s_waitcnt lgkmcnt(0)
	v_mfma_f32_16x16x32_bf16 v[120:123], v[0:3], v[184:187], v[200:203]
	v_mfma_f32_16x16x32_bf16 v[0:3], v[0:3], v[224:227], v[156:159]
	v_mfma_f32_16x16x32_bf16 v[152:155], v[4:7], v[188:191], v[120:123]
	v_mfma_f32_16x16x32_bf16 v[120:123], v[4:7], v[228:231], v[0:3]
	v_mfma_f32_16x16x32_bf16 v[0:3], v[8:11], v[184:187], v[84:87]
	v_mfma_f32_16x16x32_bf16 v[124:127], v[12:15], v[188:191], v[0:3]
	v_mfma_f32_16x16x32_bf16 v[0:3], v[8:11], v[224:227], v[80:83]
	v_mfma_f32_16x16x32_bf16 v[128:131], v[12:15], v[228:231], v[0:3]
	v_mfma_f32_16x16x32_bf16 v[0:3], v[16:19], v[184:187], v[76:79]
	v_mfma_f32_16x16x32_bf16 v[132:135], v[20:23], v[188:191], v[0:3]
	v_mfma_f32_16x16x32_bf16 v[0:3], v[16:19], v[224:227], v[72:75]
	v_mfma_f32_16x16x32_bf16 v[136:139], v[20:23], v[228:231], v[0:3]
	v_mfma_f32_16x16x32_bf16 v[0:3], v[216:219], v[184:187], v[68:71]
	v_mfma_f32_16x16x32_bf16 v[140:143], v[220:223], v[188:191], v[0:3]
	v_mfma_f32_16x16x32_bf16 v[0:3], v[216:219], v[224:227], v[64:67]
	v_mfma_f32_16x16x32_bf16 v[144:147], v[220:223], v[228:231], v[0:3]
	s_barrier
	ds_read_b128 v[64:67], v148 offset:49152
	ds_read_b128 v[68:71], v148 offset:50176
	ds_read_b128 v[72:75], v148 offset:51200
	ds_read_b128 v[76:79], v148 offset:52224
	ds_read_b128 v[80:83], v148 offset:53248
	ds_read_b128 v[84:87], v148 offset:54272
	ds_read_b128 v[156:159], v148 offset:55296
	ds_read_b128 v[148:151], v148 offset:56320
	s_barrier
	s_waitcnt lgkmcnt(0)
	s_waitcnt lgkmcnt(0)
	v_mfma_f32_16x16x32_bf16 v[0:3], v[64:67], v[24:27], v[60:63]
	v_mfma_f32_16x16x32_bf16 v[8:11], v[72:75], v[24:27], v[52:55]
	v_mfma_f32_16x16x32_bf16 v[16:19], v[80:83], v[24:27], v[44:47]
	v_mfma_f32_16x16x32_bf16 v[24:27], v[156:159], v[24:27], v[36:39]
	v_mfma_f32_16x16x32_bf16 v[0:3], v[68:71], v[28:31], v[0:3]
	v_mfma_f32_16x16x32_bf16 v[4:7], v[64:67], v[180:183], v[56:59]
	v_mfma_f32_16x16x32_bf16 v[8:11], v[76:79], v[28:31], v[8:11]
	v_mfma_f32_16x16x32_bf16 v[12:15], v[72:75], v[180:183], v[48:51]
	v_mfma_f32_16x16x32_bf16 v[16:19], v[84:87], v[28:31], v[16:19]
	v_mfma_f32_16x16x32_bf16 v[20:23], v[80:83], v[180:183], v[40:43]
	v_mfma_f32_16x16x32_bf16 v[24:27], v[148:151], v[28:31], v[24:27]
	v_mfma_f32_16x16x32_bf16 v[28:31], v[156:159], v[180:183], v[32:35]
	v_mfma_f32_16x16x32_bf16 v[4:7], v[68:71], v[196:199], v[4:7]
	v_mfma_f32_16x16x32_bf16 v[12:15], v[76:79], v[196:199], v[12:15]
	v_mfma_f32_16x16x32_bf16 v[20:23], v[84:87], v[196:199], v[20:23]
	v_mfma_f32_16x16x32_bf16 v[28:31], v[148:151], v[196:199], v[28:31]
	v_mfma_f32_16x16x32_bf16 v[32:35], v[64:67], v[184:187], v[204:207]
	v_mfma_f32_16x16x32_bf16 v[36:39], v[64:67], v[224:227], v[208:211]
	v_mfma_f32_16x16x32_bf16 v[40:43], v[72:75], v[184:187], v[212:215]
	v_mfma_f32_16x16x32_bf16 v[44:47], v[72:75], v[224:227], v[160:163]
	v_mfma_f32_16x16x32_bf16 v[48:51], v[80:83], v[184:187], v[164:167]
	v_mfma_f32_16x16x32_bf16 v[52:55], v[80:83], v[224:227], v[168:171]
	v_mfma_f32_16x16x32_bf16 v[56:59], v[156:159], v[184:187], v[172:175]
	v_mfma_f32_16x16x32_bf16 v[60:63], v[156:159], v[224:227], v[176:179]
	v_mfma_f32_16x16x32_bf16 v[32:35], v[68:71], v[188:191], v[32:35]
	v_mfma_f32_16x16x32_bf16 v[36:39], v[68:71], v[228:231], v[36:39]
	v_mfma_f32_16x16x32_bf16 v[40:43], v[76:79], v[188:191], v[40:43]
	v_mfma_f32_16x16x32_bf16 v[44:47], v[76:79], v[228:231], v[44:47]
	v_mfma_f32_16x16x32_bf16 v[48:51], v[84:87], v[188:191], v[48:51]
	v_mfma_f32_16x16x32_bf16 v[52:55], v[84:87], v[228:231], v[52:55]
	v_mfma_f32_16x16x32_bf16 v[56:59], v[148:151], v[188:191], v[56:59]
	v_mfma_f32_16x16x32_bf16 v[60:63], v[148:151], v[228:231], v[60:63]
	s_cmpk_gt_u32 s47, 0xff
	s_barrier
	s_cbranch_scc1 .LBB0_833
	s_barrier

.LBB0_836:
	v_add_u32_e32 v143, s77, v136
	ds_read_b128 v[146:149], v143
	ds_read_b128 v[150:153], v143 offset:1024
	ds_read_b128 v[154:157], v143 offset:2048
	ds_read_b128 v[158:161], v143 offset:3072
	s_add_u32 s49, s12, s38
	s_addc_u32 s53, s13, s39
	s_add_u32 s50, s49, 0x80
	s_addc_u32 s51, s53, 0
	v_add_u32_e32 v143, 0xc000, v130
	v_lshl_add_u64 v[190:191], s[50:51], 0, v[192:193]
	v_readfirstlane_b32 s50, v143
	v_add_u32_e32 v145, 0xe000, v130
	s_mov_b32 m0, s50
	v_readfirstlane_b32 s50, v145
	ds_read_b128 v[162:165], v144
	ds_read_b128 v[166:169], v144 offset:1024
	ds_read_b128 v[170:173], v144 offset:2048
	ds_read_b128 v[174:177], v144 offset:3072
	ds_read_b128 v[178:181], v144 offset:4096
	ds_read_b128 v[182:185], v144 offset:5120
	ds_read_b128 v[186:189], v144 offset:6144
	ds_read_b128 v[196:199], v144 offset:7168
	global_load_lds_dwordx4 v[190:191], off
	v_lshl_add_u64 v[190:191], v[190:191], 0, s[6:7]
	s_mov_b32 m0, s50
	s_nop 0
	global_load_lds_dwordx4 v[190:191], off
	s_waitcnt lgkmcnt(8)
	s_barrier
	s_waitcnt lgkmcnt(0)
	s_waitcnt lgkmcnt(0)
	v_mfma_f32_16x16x32_bf16 v[124:127], v[162:165], v[146:149], v[124:127]
	v_mfma_f32_16x16x32_bf16 v[120:123], v[162:165], v[154:157], v[120:123]
	v_mfma_f32_16x16x32_bf16 v[116:119], v[170:173], v[146:149], v[116:119]
	v_mfma_f32_16x16x32_bf16 v[112:115], v[170:173], v[154:157], v[112:115]
	v_mfma_f32_16x16x32_bf16 v[108:111], v[178:181], v[146:149], v[108:111]
	v_mfma_f32_16x16x32_bf16 v[104:107], v[178:181], v[154:157], v[104:107]
	v_mfma_f32_16x16x32_bf16 v[100:103], v[186:189], v[146:149], v[100:103]
	v_mfma_f32_16x16x32_bf16 v[96:99], v[186:189], v[154:157], v[96:99]
	v_mfma_f32_16x16x32_bf16 v[124:127], v[166:169], v[150:153], v[124:127]
	v_mfma_f32_16x16x32_bf16 v[120:123], v[166:169], v[158:161], v[120:123]
	v_mfma_f32_16x16x32_bf16 v[116:119], v[174:177], v[150:153], v[116:119]
	v_mfma_f32_16x16x32_bf16 v[112:115], v[174:177], v[158:161], v[112:115]
	v_mfma_f32_16x16x32_bf16 v[108:111], v[182:185], v[150:153], v[108:111]
	v_mfma_f32_16x16x32_bf16 v[104:107], v[182:185], v[158:161], v[104:107]
	v_mfma_f32_16x16x32_bf16 v[100:103], v[196:199], v[150:153], v[100:103]
	v_mfma_f32_16x16x32_bf16 v[96:99], v[196:199], v[158:161], v[96:99]
	s_barrier
	s_add_u32 s54, s0, s38
	s_addc_u32 s55, s1, s39
	s_add_u32 s50, s54, 0x100
	v_add_u32_e32 v190, s33, v136
	s_addc_u32 s51, s55, 0
	ds_read_b128 v[200:203], v190
	ds_read_b128 v[204:207], v190 offset:1024
	ds_read_b128 v[208:211], v190 offset:2048
	ds_read_b128 v[212:215], v190 offset:3072
	v_lshl_add_u64 v[190:191], s[50:51], 0, v[192:193]
	v_readfirstlane_b32 s50, v128
	s_mov_b32 m0, s50
	v_readfirstlane_b32 s50, v129
	global_load_lds_dwordx4 v[190:191], off
	v_lshl_add_u64 v[190:191], v[190:191], 0, s[6:7]
	s_mov_b32 m0, s50
	s_nop 0
	global_load_lds_dwordx4 v[190:191], off
	s_barrier
	s_waitcnt lgkmcnt(0)
	s_waitcnt lgkmcnt(0)
	v_mfma_f32_16x16x32_bf16 v[92:95], v[162:165], v[200:203], v[92:95]
	v_mfma_f32_16x16x32_bf16 v[88:91], v[162:165], v[208:211], v[88:91]
	v_mfma_f32_16x16x32_bf16 v[84:87], v[170:173], v[200:203], v[84:87]
	v_mfma_f32_16x16x32_bf16 v[80:83], v[170:173], v[208:211], v[80:83]
	v_mfma_f32_16x16x32_bf16 v[76:79], v[178:181], v[200:203], v[76:79]
	v_mfma_f32_16x16x32_bf16 v[72:75], v[178:181], v[208:211], v[72:75]
	v_mfma_f32_16x16x32_bf16 v[68:71], v[186:189], v[200:203], v[68:71]
	v_mfma_f32_16x16x32_bf16 v[64:67], v[186:189], v[208:211], v[64:67]
	v_mfma_f32_16x16x32_bf16 v[92:95], v[166:169], v[204:207], v[92:95]
	v_mfma_f32_16x16x32_bf16 v[88:91], v[166:169], v[212:215], v[88:91]
	v_mfma_f32_16x16x32_bf16 v[84:87], v[174:177], v[204:207], v[84:87]
	v_mfma_f32_16x16x32_bf16 v[80:83], v[174:177], v[212:215], v[80:83]
	v_mfma_f32_16x16x32_bf16 v[76:79], v[182:185], v[204:207], v[76:79]
	v_mfma_f32_16x16x32_bf16 v[72:75], v[182:185], v[212:215], v[72:75]
	v_mfma_f32_16x16x32_bf16 v[68:71], v[196:199], v[204:207], v[68:71]
	v_mfma_f32_16x16x32_bf16 v[64:67], v[196:199], v[212:215], v[64:67]
	s_add_u32 s72, s2, s38
	s_addc_u32 s73, s3, s39
	s_add_u32 s50, s72, 0x100
	s_addc_u32 s51, s73, 0
	v_lshl_add_u64 v[190:191], s[50:51], 0, v[192:193]
	v_readfirstlane_b32 s50, v130
	s_mov_b32 m0, s50
	v_readfirstlane_b32 s50, v131
	s_barrier
	ds_read_b128 v[162:165], v144 offset:16384
	ds_read_b128 v[166:169], v144 offset:17408
	ds_read_b128 v[170:173], v144 offset:18432
	ds_read_b128 v[174:177], v144 offset:19456
	ds_read_b128 v[178:181], v144 offset:20480
	ds_read_b128 v[182:185], v144 offset:21504
	ds_read_b128 v[186:189], v144 offset:22528
	ds_read_b128 v[196:199], v144 offset:23552
	global_load_lds_dwordx4 v[190:191], off
	v_lshl_add_u64 v[190:191], v[190:191], 0, s[6:7]
	s_mov_b32 m0, s50
	s_nop 0
	global_load_lds_dwordx4 v[190:191], off
	s_barrier
	s_waitcnt lgkmcnt(0)
	s_waitcnt lgkmcnt(0)
	v_mfma_f32_16x16x32_bf16 v[60:63], v[162:165], v[146:149], v[60:63]
	v_mfma_f32_16x16x32_bf16 v[56:59], v[162:165], v[154:157], v[56:59]
	v_mfma_f32_16x16x32_bf16 v[52:55], v[170:173], v[146:149], v[52:55]
	v_mfma_f32_16x16x32_bf16 v[48:51], v[170:173], v[154:157], v[48:51]
	v_mfma_f32_16x16x32_bf16 v[44:47], v[178:181], v[146:149], v[44:47]
	v_mfma_f32_16x16x32_bf16 v[40:43], v[178:181], v[154:157], v[40:43]
	v_mfma_f32_16x16x32_bf16 v[36:39], v[186:189], v[146:149], v[36:39]
	v_mfma_f32_16x16x32_bf16 v[32:35], v[186:189], v[154:157], v[32:35]
	v_mfma_f32_16x16x32_bf16 v[60:63], v[166:169], v[150:153], v[60:63]
	v_mfma_f32_16x16x32_bf16 v[56:59], v[166:169], v[158:161], v[56:59]
	v_mfma_f32_16x16x32_bf16 v[52:55], v[174:177], v[150:153], v[52:55]
	v_mfma_f32_16x16x32_bf16 v[48:51], v[174:177], v[158:161], v[48:51]
	v_mfma_f32_16x16x32_bf16 v[44:47], v[182:185], v[150:153], v[44:47]
	v_mfma_f32_16x16x32_bf16 v[40:43], v[182:185], v[158:161], v[40:43]
	v_mfma_f32_16x16x32_bf16 v[36:39], v[196:199], v[150:153], v[36:39]
	v_mfma_f32_16x16x32_bf16 v[32:35], v[196:199], v[158:161], v[32:35]
	s_barrier
	s_add_u32 s74, s36, s38
	s_addc_u32 s75, s37, s39
	s_add_u32 s50, s74, 0x100
	s_addc_u32 s51, s75, 0
	v_lshl_add_u64 v[146:147], s[50:51], 0, v[192:193]
	v_readfirstlane_b32 s50, v132
	s_mov_b32 m0, s50
	v_readfirstlane_b32 s50, v133
	global_load_lds_dwordx4 v[146:147], off
	v_lshl_add_u64 v[146:147], v[146:147], 0, s[6:7]
	s_mov_b32 m0, s50
	s_nop 0
	global_load_lds_dwordx4 v[146:147], off
	s_waitcnt vmcnt(6)
	s_barrier
	v_mfma_f32_16x16x32_bf16 v[28:31], v[162:165], v[200:203], v[28:31]
	v_mfma_f32_16x16x32_bf16 v[24:27], v[162:165], v[208:211], v[24:27]
	v_mfma_f32_16x16x32_bf16 v[20:23], v[170:173], v[200:203], v[20:23]
	v_mfma_f32_16x16x32_bf16 v[16:19], v[170:173], v[208:211], v[16:19]
	v_mfma_f32_16x16x32_bf16 v[12:15], v[178:181], v[200:203], v[12:15]
	v_mfma_f32_16x16x32_bf16 v[8:11], v[178:181], v[208:211], v[8:11]
	v_mfma_f32_16x16x32_bf16 v[4:7], v[186:189], v[200:203], v[4:7]
	v_mfma_f32_16x16x32_bf16 v[0:3], v[186:189], v[208:211], v[0:3]
	v_mfma_f32_16x16x32_bf16 v[28:31], v[166:169], v[204:207], v[28:31]
	v_mfma_f32_16x16x32_bf16 v[24:27], v[166:169], v[212:215], v[24:27]
	v_mfma_f32_16x16x32_bf16 v[20:23], v[174:177], v[204:207], v[20:23]
	v_mfma_f32_16x16x32_bf16 v[16:19], v[174:177], v[212:215], v[16:19]
	v_mfma_f32_16x16x32_bf16 v[12:15], v[182:185], v[204:207], v[12:15]
	v_mfma_f32_16x16x32_bf16 v[8:11], v[182:185], v[212:215], v[8:11]
	v_mfma_f32_16x16x32_bf16 v[4:7], v[196:199], v[204:207], v[4:7]
	v_mfma_f32_16x16x32_bf16 v[0:3], v[196:199], v[212:215], v[0:3]
	v_add_u32_e32 v158, s93, v136
	s_barrier
	ds_read_b128 v[146:149], v158
	ds_read_b128 v[150:153], v158 offset:1024
	ds_read_b128 v[154:157], v158 offset:2048
	ds_read_b128 v[158:161], v158 offset:3072
	s_add_u32 s50, s49, 0x100
	s_addc_u32 s51, s53, 0
	v_readfirstlane_b32 s49, v134
	v_lshl_add_u64 v[190:191], s[50:51], 0, v[192:193]
	s_mov_b32 m0, s49
	v_readfirstlane_b32 s49, v135
	ds_read_b128 v[162:165], v144 offset:32768
	ds_read_b128 v[166:169], v144 offset:33792
	ds_read_b128 v[170:173], v144 offset:34816
	ds_read_b128 v[174:177], v144 offset:35840
	ds_read_b128 v[178:181], v144 offset:36864
	ds_read_b128 v[182:185], v144 offset:37888
	ds_read_b128 v[186:189], v144 offset:38912
	ds_read_b128 v[196:199], v144 offset:39936
	global_load_lds_dwordx4 v[190:191], off
	v_lshl_add_u64 v[190:191], v[190:191], 0, s[6:7]
	s_mov_b32 m0, s49
	s_nop 0
	global_load_lds_dwordx4 v[190:191], off
	s_waitcnt lgkmcnt(8)
	s_barrier
	s_waitcnt lgkmcnt(0)
	s_waitcnt lgkmcnt(0)
	v_mfma_f32_16x16x32_bf16 v[124:127], v[162:165], v[146:149], v[124:127]
	v_mfma_f32_16x16x32_bf16 v[120:123], v[162:165], v[154:157], v[120:123]
	v_mfma_f32_16x16x32_bf16 v[116:119], v[170:173], v[146:149], v[116:119]
	v_mfma_f32_16x16x32_bf16 v[112:115], v[170:173], v[154:157], v[112:115]
	v_mfma_f32_16x16x32_bf16 v[108:111], v[178:181], v[146:149], v[108:111]
	v_mfma_f32_16x16x32_bf16 v[104:107], v[178:181], v[154:157], v[104:107]
	v_mfma_f32_16x16x32_bf16 v[100:103], v[186:189], v[146:149], v[100:103]
	v_mfma_f32_16x16x32_bf16 v[96:99], v[186:189], v[154:157], v[96:99]
	v_mfma_f32_16x16x32_bf16 v[124:127], v[166:169], v[150:153], v[124:127]
	v_mfma_f32_16x16x32_bf16 v[120:123], v[166:169], v[158:161], v[120:123]
	v_mfma_f32_16x16x32_bf16 v[116:119], v[174:177], v[150:153], v[116:119]
	v_mfma_f32_16x16x32_bf16 v[112:115], v[174:177], v[158:161], v[112:115]
	v_mfma_f32_16x16x32_bf16 v[108:111], v[182:185], v[150:153], v[108:111]
	v_mfma_f32_16x16x32_bf16 v[104:107], v[182:185], v[158:161], v[104:107]
	v_mfma_f32_16x16x32_bf16 v[100:103], v[196:199], v[150:153], v[100:103]
	v_mfma_f32_16x16x32_bf16 v[96:99], v[196:199], v[158:161], v[96:99]
	s_barrier
	s_add_u32 s50, s54, 0x180
	v_add_u32_e32 v190, s89, v136
	s_addc_u32 s51, s55, 0
	v_readfirstlane_b32 s49, v137
	ds_read_b128 v[200:203], v190
	ds_read_b128 v[204:207], v190 offset:1024
	ds_read_b128 v[208:211], v190 offset:2048
	ds_read_b128 v[212:215], v190 offset:3072
	v_lshl_add_u64 v[190:191], s[50:51], 0, v[192:193]
	s_mov_b32 m0, s49
	v_readfirstlane_b32 s49, v138
	global_load_lds_dwordx4 v[190:191], off
	v_lshl_add_u64 v[190:191], v[190:191], 0, s[6:7]
	s_mov_b32 m0, s49
	s_nop 0
	global_load_lds_dwordx4 v[190:191], off
	s_barrier
	s_waitcnt lgkmcnt(0)
	s_waitcnt lgkmcnt(0)
	v_mfma_f32_16x16x32_bf16 v[92:95], v[162:165], v[200:203], v[92:95]
	v_mfma_f32_16x16x32_bf16 v[88:91], v[162:165], v[208:211], v[88:91]
	v_mfma_f32_16x16x32_bf16 v[84:87], v[170:173], v[200:203], v[84:87]
	v_mfma_f32_16x16x32_bf16 v[80:83], v[170:173], v[208:211], v[80:83]
	v_mfma_f32_16x16x32_bf16 v[76:79], v[178:181], v[200:203], v[76:79]
	v_mfma_f32_16x16x32_bf16 v[72:75], v[178:181], v[208:211], v[72:75]
	v_mfma_f32_16x16x32_bf16 v[68:71], v[186:189], v[200:203], v[68:71]
	v_mfma_f32_16x16x32_bf16 v[64:67], v[186:189], v[208:211], v[64:67]
	v_mfma_f32_16x16x32_bf16 v[92:95], v[166:169], v[204:207], v[92:95]
	v_mfma_f32_16x16x32_bf16 v[88:91], v[166:169], v[212:215], v[88:91]
	v_mfma_f32_16x16x32_bf16 v[84:87], v[174:177], v[204:207], v[84:87]
	v_mfma_f32_16x16x32_bf16 v[80:83], v[174:177], v[212:215], v[80:83]
	v_mfma_f32_16x16x32_bf16 v[76:79], v[182:185], v[204:207], v[76:79]
	v_mfma_f32_16x16x32_bf16 v[72:75], v[182:185], v[212:215], v[72:75]
	v_mfma_f32_16x16x32_bf16 v[68:71], v[196:199], v[204:207], v[68:71]
	v_mfma_f32_16x16x32_bf16 v[64:67], v[196:199], v[212:215], v[64:67]
	s_add_u32 s50, s72, 0x180
	s_addc_u32 s51, s73, 0
	v_readfirstlane_b32 s49, v139
	v_lshl_add_u64 v[190:191], s[50:51], 0, v[192:193]
	s_mov_b32 m0, s49
	v_readfirstlane_b32 s49, v140
	s_barrier
	ds_read_b128 v[162:165], v144 offset:49152
	ds_read_b128 v[166:169], v144 offset:50176
	ds_read_b128 v[170:173], v144 offset:51200
	ds_read_b128 v[174:177], v144 offset:52224
	ds_read_b128 v[178:181], v144 offset:53248
	ds_read_b128 v[182:185], v144 offset:54272
	ds_read_b128 v[186:189], v144 offset:55296
	ds_read_b128 v[196:199], v144 offset:56320
	global_load_lds_dwordx4 v[190:191], off
	v_lshl_add_u64 v[190:191], v[190:191], 0, s[6:7]
	s_mov_b32 m0, s49
	s_nop 0
	global_load_lds_dwordx4 v[190:191], off
	s_barrier
	s_waitcnt lgkmcnt(0)
	s_waitcnt lgkmcnt(0)
	v_mfma_f32_16x16x32_bf16 v[60:63], v[162:165], v[146:149], v[60:63]
	v_mfma_f32_16x16x32_bf16 v[56:59], v[162:165], v[154:157], v[56:59]
	v_mfma_f32_16x16x32_bf16 v[52:55], v[170:173], v[146:149], v[52:55]
	v_mfma_f32_16x16x32_bf16 v[48:51], v[170:173], v[154:157], v[48:51]
	v_mfma_f32_16x16x32_bf16 v[44:47], v[178:181], v[146:149], v[44:47]
	v_mfma_f32_16x16x32_bf16 v[40:43], v[178:181], v[154:157], v[40:43]
	v_mfma_f32_16x16x32_bf16 v[36:39], v[186:189], v[146:149], v[36:39]
	v_mfma_f32_16x16x32_bf16 v[32:35], v[186:189], v[154:157], v[32:35]
	v_mfma_f32_16x16x32_bf16 v[60:63], v[166:169], v[150:153], v[60:63]
	v_mfma_f32_16x16x32_bf16 v[56:59], v[166:169], v[158:161], v[56:59]
	v_mfma_f32_16x16x32_bf16 v[52:55], v[174:177], v[150:153], v[52:55]
	v_mfma_f32_16x16x32_bf16 v[48:51], v[174:177], v[158:161], v[48:51]
	v_mfma_f32_16x16x32_bf16 v[44:47], v[182:185], v[150:153], v[44:47]
	v_mfma_f32_16x16x32_bf16 v[40:43], v[182:185], v[158:161], v[40:43]
	v_mfma_f32_16x16x32_bf16 v[36:39], v[196:199], v[150:153], v[36:39]
	v_mfma_f32_16x16x32_bf16 v[32:35], v[196:199], v[158:161], v[32:35]
	s_barrier
	s_add_u32 s50, s74, 0x180
	s_addc_u32 s51, s75, 0
	v_readfirstlane_b32 s49, v141
	v_lshl_add_u64 v[146:147], s[50:51], 0, v[192:193]
	s_mov_b32 m0, s49
	v_readfirstlane_b32 s49, v142
	global_load_lds_dwordx4 v[146:147], off
	v_lshl_add_u64 v[146:147], v[146:147], 0, s[6:7]
	s_mov_b32 m0, s49
	s_nop 0
	global_load_lds_dwordx4 v[146:147], off
	s_waitcnt vmcnt(6)
	s_barrier
	v_mfma_f32_16x16x32_bf16 v[28:31], v[162:165], v[200:203], v[28:31]
	v_mfma_f32_16x16x32_bf16 v[24:27], v[162:165], v[208:211], v[24:27]
	v_mfma_f32_16x16x32_bf16 v[20:23], v[170:173], v[200:203], v[20:23]
	v_mfma_f32_16x16x32_bf16 v[16:19], v[170:173], v[208:211], v[16:19]
	v_mfma_f32_16x16x32_bf16 v[12:15], v[178:181], v[200:203], v[12:15]
	v_mfma_f32_16x16x32_bf16 v[8:11], v[178:181], v[208:211], v[8:11]
	v_mfma_f32_16x16x32_bf16 v[4:7], v[186:189], v[200:203], v[4:7]
	v_mfma_f32_16x16x32_bf16 v[0:3], v[186:189], v[208:211], v[0:3]
	v_mfma_f32_16x16x32_bf16 v[28:31], v[166:169], v[204:207], v[28:31]
	v_mfma_f32_16x16x32_bf16 v[24:27], v[166:169], v[212:215], v[24:27]
	v_mfma_f32_16x16x32_bf16 v[20:23], v[174:177], v[204:207], v[20:23]
	v_mfma_f32_16x16x32_bf16 v[16:19], v[174:177], v[212:215], v[16:19]
	v_mfma_f32_16x16x32_bf16 v[12:15], v[182:185], v[204:207], v[12:15]
	v_mfma_f32_16x16x32_bf16 v[8:11], v[182:185], v[212:215], v[8:11]
	v_mfma_f32_16x16x32_bf16 v[4:7], v[196:199], v[204:207], v[4:7]
	v_mfma_f32_16x16x32_bf16 v[0:3], v[196:199], v[212:215], v[0:3]
	s_add_i32 s48, s48, 2
	s_add_u32 s38, s38, 0x100
	s_addc_u32 s39, s39, 0
	s_cmp_lt_u32 s48, 4
	s_barrier
	s_cbranch_scc1 .LBB0_836
	v_add_u32_e32 v195, 0, v136
	s_add_u32 s0, s12, 0x380
	v_add_u32_e32 v140, 0x10000, v195
	s_addc_u32 s1, s13, 0
	ds_read_b128 v[128:131], v140
	ds_read_b128 v[132:135], v140 offset:1024
	ds_read_b128 v[136:139], v140 offset:2048
	ds_read_b128 v[146:149], v140 offset:3072
	ds_read_b128 v[150:153], v144
	ds_read_b128 v[154:157], v144 offset:1024
	ds_read_b128 v[158:161], v144 offset:2048
	ds_read_b128 v[162:165], v144 offset:3072
	ds_read_b128 v[166:169], v144 offset:4096
	ds_read_b128 v[170:173], v144 offset:5120
	ds_read_b128 v[174:177], v144 offset:6144
	ds_read_b128 v[178:181], v144 offset:7168
	v_lshl_add_u64 v[140:141], s[0:1], 0, v[192:193]
	v_readfirstlane_b32 s0, v143
	s_mov_b32 m0, s0
	v_readfirstlane_b32 s0, v145
	global_load_lds_dwordx4 v[140:141], off
	v_lshl_add_u64 v[140:141], v[140:141], 0, s[6:7]
	s_mov_b32 m0, s0
	s_nop 0
	global_load_lds_dwordx4 v[140:141], off
	s_barrier
	s_waitcnt lgkmcnt(0)
	s_waitcnt lgkmcnt(0)
	v_mfma_f32_16x16x32_bf16 v[124:127], v[150:153], v[128:131], v[124:127]
	v_mfma_f32_16x16x32_bf16 v[120:123], v[150:153], v[136:139], v[120:123]
	v_mfma_f32_16x16x32_bf16 v[116:119], v[158:161], v[128:131], v[116:119]
	v_mfma_f32_16x16x32_bf16 v[124:127], v[154:157], v[132:135], v[124:127]
	v_mfma_f32_16x16x32_bf16 v[120:123], v[154:157], v[146:149], v[120:123]
	v_mfma_f32_16x16x32_bf16 v[140:143], v[162:165], v[132:135], v[116:119]
	v_mfma_f32_16x16x32_bf16 v[112:115], v[158:161], v[136:139], v[112:115]
	v_mfma_f32_16x16x32_bf16 v[108:111], v[166:169], v[128:131], v[108:111]
	v_mfma_f32_16x16x32_bf16 v[104:107], v[166:169], v[136:139], v[104:107]
	v_mfma_f32_16x16x32_bf16 v[100:103], v[174:177], v[128:131], v[100:103]
	v_mfma_f32_16x16x32_bf16 v[96:99], v[174:177], v[136:139], v[96:99]
	v_mfma_f32_16x16x32_bf16 v[112:115], v[162:165], v[146:149], v[112:115]
	v_mfma_f32_16x16x32_bf16 v[108:111], v[170:173], v[132:135], v[108:111]
	v_mfma_f32_16x16x32_bf16 v[104:107], v[170:173], v[146:149], v[104:107]
	v_mfma_f32_16x16x32_bf16 v[100:103], v[178:181], v[132:135], v[100:103]
	v_mfma_f32_16x16x32_bf16 v[96:99], v[178:181], v[146:149], v[96:99]
	v_add_u32_e32 v145, 0x14000, v195
	s_barrier
	ds_read_b128 v[116:119], v145
	ds_read_b128 v[182:185], v145 offset:1024
	ds_read_b128 v[186:189], v145 offset:2048
	ds_read_b128 v[196:199], v145 offset:3072
	s_barrier
	s_waitcnt lgkmcnt(0)
	s_waitcnt lgkmcnt(0)
	v_mfma_f32_16x16x32_bf16 v[92:95], v[150:153], v[116:119], v[92:95]
	v_mfma_f32_16x16x32_bf16 v[88:91], v[150:153], v[186:189], v[88:91]
	v_mfma_f32_16x16x32_bf16 v[84:87], v[158:161], v[116:119], v[84:87]
	v_mfma_f32_16x16x32_bf16 v[80:83], v[158:161], v[186:189], v[80:83]
	v_mfma_f32_16x16x32_bf16 v[76:79], v[166:169], v[116:119], v[76:79]
	v_mfma_f32_16x16x32_bf16 v[72:75], v[166:169], v[186:189], v[72:75]
	v_mfma_f32_16x16x32_bf16 v[68:71], v[174:177], v[116:119], v[68:71]
	v_mfma_f32_16x16x32_bf16 v[64:67], v[174:177], v[186:189], v[64:67]
	v_mfma_f32_16x16x32_bf16 v[92:95], v[154:157], v[182:185], v[92:95]
	v_mfma_f32_16x16x32_bf16 v[88:91], v[154:157], v[196:199], v[88:91]
	v_mfma_f32_16x16x32_bf16 v[84:87], v[162:165], v[182:185], v[84:87]
	v_mfma_f32_16x16x32_bf16 v[80:83], v[162:165], v[196:199], v[80:83]
	v_mfma_f32_16x16x32_bf16 v[76:79], v[170:173], v[182:185], v[76:79]
	v_mfma_f32_16x16x32_bf16 v[72:75], v[170:173], v[196:199], v[72:75]
	v_mfma_f32_16x16x32_bf16 v[68:71], v[178:181], v[182:185], v[68:71]
	v_mfma_f32_16x16x32_bf16 v[64:67], v[178:181], v[196:199], v[64:67]
	s_barrier
	ds_read_b128 v[150:153], v144 offset:16384
	ds_read_b128 v[154:157], v144 offset:17408
	ds_read_b128 v[158:161], v144 offset:18432
	ds_read_b128 v[162:165], v144 offset:19456
	ds_read_b128 v[166:169], v144 offset:20480
	ds_read_b128 v[170:173], v144 offset:21504
	ds_read_b128 v[174:177], v144 offset:22528
	ds_read_b128 v[178:181], v144 offset:23552
	s_waitcnt vmcnt(4)
	s_barrier
	s_waitcnt lgkmcnt(0)
	s_waitcnt lgkmcnt(0)
	v_mfma_f32_16x16x32_bf16 v[60:63], v[150:153], v[128:131], v[60:63]
	v_mfma_f32_16x16x32_bf16 v[56:59], v[150:153], v[136:139], v[56:59]
	v_mfma_f32_16x16x32_bf16 v[52:55], v[158:161], v[128:131], v[52:55]
	v_mfma_f32_16x16x32_bf16 v[48:51], v[158:161], v[136:139], v[48:51]
	v_mfma_f32_16x16x32_bf16 v[44:47], v[166:169], v[128:131], v[44:47]
	v_mfma_f32_16x16x32_bf16 v[40:43], v[166:169], v[136:139], v[40:43]
	v_mfma_f32_16x16x32_bf16 v[36:39], v[174:177], v[128:131], v[36:39]
	v_mfma_f32_16x16x32_bf16 v[32:35], v[174:177], v[136:139], v[32:35]
	v_mfma_f32_16x16x32_bf16 v[60:63], v[154:157], v[132:135], v[60:63]
	v_mfma_f32_16x16x32_bf16 v[56:59], v[154:157], v[146:149], v[56:59]
	v_mfma_f32_16x16x32_bf16 v[52:55], v[162:165], v[132:135], v[52:55]
	v_mfma_f32_16x16x32_bf16 v[48:51], v[162:165], v[146:149], v[48:51]
	v_mfma_f32_16x16x32_bf16 v[44:47], v[170:173], v[132:135], v[44:47]
	v_mfma_f32_16x16x32_bf16 v[40:43], v[170:173], v[146:149], v[40:43]
	v_mfma_f32_16x16x32_bf16 v[36:39], v[178:181], v[132:135], v[36:39]
	v_mfma_f32_16x16x32_bf16 v[32:35], v[178:181], v[146:149], v[32:35]
	v_mfma_f32_16x16x32_bf16 v[28:31], v[150:153], v[116:119], v[28:31]
	v_mfma_f32_16x16x32_bf16 v[24:27], v[150:153], v[186:189], v[24:27]
	v_mfma_f32_16x16x32_bf16 v[20:23], v[158:161], v[116:119], v[20:23]
	v_mfma_f32_16x16x32_bf16 v[16:19], v[158:161], v[186:189], v[16:19]
	v_mfma_f32_16x16x32_bf16 v[12:15], v[166:169], v[116:119], v[12:15]
	v_mfma_f32_16x16x32_bf16 v[8:11], v[166:169], v[186:189], v[8:11]
	v_mfma_f32_16x16x32_bf16 v[4:7], v[174:177], v[116:119], v[4:7]
	v_mfma_f32_16x16x32_bf16 v[0:3], v[174:177], v[186:189], v[0:3]
	v_mfma_f32_16x16x32_bf16 v[200:203], v[154:157], v[182:185], v[28:31]
	v_mfma_f32_16x16x32_bf16 v[204:207], v[154:157], v[196:199], v[24:27]
	v_mfma_f32_16x16x32_bf16 v[208:211], v[162:165], v[182:185], v[20:23]
	v_mfma_f32_16x16x32_bf16 v[212:215], v[162:165], v[196:199], v[16:19]
	v_mfma_f32_16x16x32_bf16 v[216:219], v[170:173], v[182:185], v[12:15]
	v_mfma_f32_16x16x32_bf16 v[220:223], v[170:173], v[196:199], v[8:11]
	v_mfma_f32_16x16x32_bf16 v[224:227], v[178:181], v[182:185], v[4:7]
	v_mfma_f32_16x16x32_bf16 v[184:187], v[178:181], v[196:199], v[0:3]
	s_nop 1
	v_add_u32_e32 v0, 0x18000, v195
	s_barrier
	ds_read_b128 v[24:27], v0
	ds_read_b128 v[28:31], v0 offset:1024
	ds_read_b128 v[188:191], v0 offset:2048
	ds_read_b128 v[196:199], v0 offset:3072
	ds_read_b128 v[0:3], v144 offset:32768
	ds_read_b128 v[4:7], v144 offset:33792
	ds_read_b128 v[8:11], v144 offset:34816
	ds_read_b128 v[12:15], v144 offset:35840
	ds_read_b128 v[16:19], v144 offset:36864
	ds_read_b128 v[20:23], v144 offset:37888
	ds_read_b128 v[176:179], v144 offset:38912
	ds_read_b128 v[228:231], v144 offset:39936
	s_waitcnt vmcnt(2)
	s_barrier
	s_waitcnt lgkmcnt(0)
	s_waitcnt lgkmcnt(0)
	v_mfma_f32_16x16x32_bf16 v[116:119], v[0:3], v[24:27], v[124:127]
	v_mfma_f32_16x16x32_bf16 v[148:151], v[4:7], v[28:31], v[116:119]
	v_mfma_f32_16x16x32_bf16 v[116:119], v[0:3], v[188:191], v[120:123]
	v_mfma_f32_16x16x32_bf16 v[120:123], v[8:11], v[24:27], v[140:143]
	v_mfma_f32_16x16x32_bf16 v[112:115], v[8:11], v[188:191], v[112:115]
	v_mfma_f32_16x16x32_bf16 v[108:111], v[16:19], v[24:27], v[108:111]
	v_mfma_f32_16x16x32_bf16 v[104:107], v[16:19], v[188:191], v[104:107]
	v_mfma_f32_16x16x32_bf16 v[100:103], v[176:179], v[24:27], v[100:103]
	v_mfma_f32_16x16x32_bf16 v[96:99], v[176:179], v[188:191], v[96:99]
	v_mfma_f32_16x16x32_bf16 v[116:119], v[4:7], v[196:199], v[116:119]
	v_mfma_f32_16x16x32_bf16 v[120:123], v[12:15], v[28:31], v[120:123]
	v_mfma_f32_16x16x32_bf16 v[124:127], v[12:15], v[196:199], v[112:115]
	v_mfma_f32_16x16x32_bf16 v[128:131], v[20:23], v[28:31], v[108:111]
	v_mfma_f32_16x16x32_bf16 v[132:135], v[20:23], v[196:199], v[104:107]
	v_mfma_f32_16x16x32_bf16 v[136:139], v[228:231], v[28:31], v[100:103]
	v_mfma_f32_16x16x32_bf16 v[140:143], v[228:231], v[196:199], v[96:99]
	v_add_u32_e32 v108, 0x1c000, v195
	s_barrier
	ds_read_b128 v[96:99], v108
	ds_read_b128 v[100:103], v108 offset:1024
	ds_read_b128 v[104:107], v108 offset:2048
	ds_read_b128 v[108:111], v108 offset:3072
	s_waitcnt vmcnt(0)
	s_barrier
	s_waitcnt lgkmcnt(0)
	s_waitcnt lgkmcnt(0)
	v_mfma_f32_16x16x32_bf16 v[92:95], v[0:3], v[96:99], v[92:95]
	v_mfma_f32_16x16x32_bf16 v[0:3], v[0:3], v[104:107], v[88:91]
	v_mfma_f32_16x16x32_bf16 v[152:155], v[4:7], v[108:111], v[0:3]
	v_mfma_f32_16x16x32_bf16 v[0:3], v[8:11], v[96:99], v[84:87]
	v_mfma_f32_16x16x32_bf16 v[156:159], v[12:15], v[100:103], v[0:3]
	v_mfma_f32_16x16x32_bf16 v[0:3], v[8:11], v[104:107], v[80:83]
	v_mfma_f32_16x16x32_bf16 v[160:163], v[12:15], v[108:111], v[0:3]
	v_mfma_f32_16x16x32_bf16 v[0:3], v[16:19], v[96:99], v[76:79]
	v_mfma_f32_16x16x32_bf16 v[164:167], v[20:23], v[100:103], v[0:3]
	v_mfma_f32_16x16x32_bf16 v[0:3], v[16:19], v[104:107], v[72:75]
	v_mfma_f32_16x16x32_bf16 v[168:171], v[20:23], v[108:111], v[0:3]
	v_mfma_f32_16x16x32_bf16 v[0:3], v[176:179], v[96:99], v[68:71]
	v_mfma_f32_16x16x32_bf16 v[172:175], v[228:231], v[100:103], v[0:3]
	v_mfma_f32_16x16x32_bf16 v[0:3], v[176:179], v[104:107], v[64:67]
	v_mfma_f32_16x16x32_bf16 v[180:183], v[4:7], v[100:103], v[92:95]
	v_mfma_f32_16x16x32_bf16 v[176:179], v[228:231], v[108:111], v[0:3]
	s_barrier
	ds_read_b128 v[64:67], v144 offset:49152
	ds_read_b128 v[68:71], v144 offset:50176
	ds_read_b128 v[72:75], v144 offset:51200
	ds_read_b128 v[76:79], v144 offset:52224
	ds_read_b128 v[80:83], v144 offset:53248
	ds_read_b128 v[84:87], v144 offset:54272
	ds_read_b128 v[88:91], v144 offset:55296
	ds_read_b128 v[92:95], v144 offset:56320
	s_barrier
	s_waitcnt lgkmcnt(0)
	s_waitcnt lgkmcnt(0)
	v_mfma_f32_16x16x32_bf16 v[0:3], v[64:67], v[24:27], v[60:63]
	v_mfma_f32_16x16x32_bf16 v[8:11], v[72:75], v[24:27], v[52:55]
	v_mfma_f32_16x16x32_bf16 v[16:19], v[80:83], v[24:27], v[44:47]
	v_mfma_f32_16x16x32_bf16 v[24:27], v[88:91], v[24:27], v[36:39]
	v_mfma_f32_16x16x32_bf16 v[0:3], v[68:71], v[28:31], v[0:3]
	v_mfma_f32_16x16x32_bf16 v[4:7], v[64:67], v[188:191], v[56:59]
	v_mfma_f32_16x16x32_bf16 v[8:11], v[76:79], v[28:31], v[8:11]
	v_mfma_f32_16x16x32_bf16 v[12:15], v[72:75], v[188:191], v[48:51]
	v_mfma_f32_16x16x32_bf16 v[16:19], v[84:87], v[28:31], v[16:19]
	v_mfma_f32_16x16x32_bf16 v[20:23], v[80:83], v[188:191], v[40:43]
	v_mfma_f32_16x16x32_bf16 v[24:27], v[92:95], v[28:31], v[24:27]
	v_mfma_f32_16x16x32_bf16 v[28:31], v[88:91], v[188:191], v[32:35]
	v_mfma_f32_16x16x32_bf16 v[4:7], v[68:71], v[196:199], v[4:7]
	v_mfma_f32_16x16x32_bf16 v[12:15], v[76:79], v[196:199], v[12:15]
	v_mfma_f32_16x16x32_bf16 v[20:23], v[84:87], v[196:199], v[20:23]
	v_mfma_f32_16x16x32_bf16 v[28:31], v[92:95], v[196:199], v[28:31]
	v_mfma_f32_16x16x32_bf16 v[32:35], v[64:67], v[96:99], v[200:203]
	v_mfma_f32_16x16x32_bf16 v[36:39], v[64:67], v[104:107], v[204:207]
	v_mfma_f32_16x16x32_bf16 v[40:43], v[72:75], v[96:99], v[208:211]
	v_mfma_f32_16x16x32_bf16 v[44:47], v[72:75], v[104:107], v[212:215]
	v_mfma_f32_16x16x32_bf16 v[48:51], v[80:83], v[96:99], v[216:219]
	v_mfma_f32_16x16x32_bf16 v[52:55], v[80:83], v[104:107], v[220:223]
	v_mfma_f32_16x16x32_bf16 v[56:59], v[88:91], v[96:99], v[224:227]
	v_mfma_f32_16x16x32_bf16 v[60:63], v[88:91], v[104:107], v[184:187]
	v_mfma_f32_16x16x32_bf16 v[32:35], v[68:71], v[100:103], v[32:35]
	v_mfma_f32_16x16x32_bf16 v[36:39], v[68:71], v[108:111], v[36:39]
	v_mfma_f32_16x16x32_bf16 v[40:43], v[76:79], v[100:103], v[40:43]
	v_mfma_f32_16x16x32_bf16 v[44:47], v[76:79], v[108:111], v[44:47]
	v_mfma_f32_16x16x32_bf16 v[48:51], v[84:87], v[100:103], v[48:51]
	v_mfma_f32_16x16x32_bf16 v[52:55], v[84:87], v[108:111], v[52:55]
	v_mfma_f32_16x16x32_bf16 v[56:59], v[92:95], v[100:103], v[56:59]
	v_mfma_f32_16x16x32_bf16 v[60:63], v[92:95], v[108:111], v[60:63]
	s_cmpk_gt_u32 s52, 0xff
	s_barrier
	s_cbranch_scc1 .LBB0_826
	s_barrier
	s_branch .LBB0_826

.LBB0_1020:
	v_add_u32_e32 v143, s77, v136
	ds_read_b128 v[146:149], v143
	ds_read_b128 v[150:153], v143 offset:1024
	ds_read_b128 v[154:157], v143 offset:2048
	ds_read_b128 v[158:161], v143 offset:3072
	s_add_u32 s13, s46, s48
	s_addc_u32 s72, s47, s49
	s_add_u32 s54, s13, 0x80
	s_addc_u32 s55, s72, 0
	v_add_u32_e32 v143, 0xc000, v130
	v_lshl_add_u64 v[144:145], s[54:55], 0, v[192:193]
	v_readfirstlane_b32 s54, v143
	s_mov_b32 m0, s54
	ds_read_b128 v[162:165], v195
	ds_read_b128 v[166:169], v195 offset:1024
	ds_read_b128 v[170:173], v195 offset:2048
	ds_read_b128 v[174:177], v195 offset:3072
	ds_read_b128 v[178:181], v195 offset:4096
	ds_read_b128 v[182:185], v195 offset:5120
	ds_read_b128 v[186:189], v195 offset:6144
	ds_read_b128 v[196:199], v195 offset:7168
	global_load_lds_dwordx4 v[144:145], off
	v_lshl_add_u64 v[190:191], v[144:145], 0, s[34:35]
	v_add_u32_e32 v144, 0xe000, v130
	s_nop 0
	v_readfirstlane_b32 s54, v144
	s_mov_b32 m0, s54
	s_nop 0
	global_load_lds_dwordx4 v[190:191], off
	s_waitcnt lgkmcnt(8)
	s_barrier
	s_waitcnt lgkmcnt(0)
	s_waitcnt lgkmcnt(0)
	v_mfma_f32_16x16x32_bf16 v[124:127], v[162:165], v[146:149], v[124:127]
	v_mfma_f32_16x16x32_bf16 v[120:123], v[162:165], v[154:157], v[120:123]
	v_mfma_f32_16x16x32_bf16 v[116:119], v[170:173], v[146:149], v[116:119]
	v_mfma_f32_16x16x32_bf16 v[112:115], v[170:173], v[154:157], v[112:115]
	v_mfma_f32_16x16x32_bf16 v[108:111], v[178:181], v[146:149], v[108:111]
	v_mfma_f32_16x16x32_bf16 v[104:107], v[178:181], v[154:157], v[104:107]
	v_mfma_f32_16x16x32_bf16 v[100:103], v[186:189], v[146:149], v[100:103]
	v_mfma_f32_16x16x32_bf16 v[96:99], v[186:189], v[154:157], v[96:99]
	v_mfma_f32_16x16x32_bf16 v[124:127], v[166:169], v[150:153], v[124:127]
	v_mfma_f32_16x16x32_bf16 v[120:123], v[166:169], v[158:161], v[120:123]
	v_mfma_f32_16x16x32_bf16 v[116:119], v[174:177], v[150:153], v[116:119]
	v_mfma_f32_16x16x32_bf16 v[112:115], v[174:177], v[158:161], v[112:115]
	v_mfma_f32_16x16x32_bf16 v[108:111], v[182:185], v[150:153], v[108:111]
	v_mfma_f32_16x16x32_bf16 v[104:107], v[182:185], v[158:161], v[104:107]
	v_mfma_f32_16x16x32_bf16 v[100:103], v[196:199], v[150:153], v[100:103]
	v_mfma_f32_16x16x32_bf16 v[96:99], v[196:199], v[158:161], v[96:99]
	s_barrier
	s_add_u32 s73, s38, s48
	s_addc_u32 s74, s39, s49
	s_add_u32 s54, s73, 0x100
	s_addc_u32 s55, s74, 0
	v_lshl_add_u64 v[190:191], s[54:55], 0, v[192:193]
	v_readfirstlane_b32 s54, v128
	v_add_u32_e32 v145, s33, v136
	s_mov_b32 m0, s54
	v_readfirstlane_b32 s54, v129
	ds_read_b128 v[200:203], v145
	ds_read_b128 v[204:207], v145 offset:1024
	ds_read_b128 v[208:211], v145 offset:2048
	ds_read_b128 v[212:215], v145 offset:3072
	global_load_lds_dwordx4 v[190:191], off
	v_lshl_add_u64 v[190:191], v[190:191], 0, s[34:35]
	s_mov_b32 m0, s54
	s_nop 0
	global_load_lds_dwordx4 v[190:191], off
	s_barrier
	s_waitcnt lgkmcnt(0)
	s_waitcnt lgkmcnt(0)
	v_mfma_f32_16x16x32_bf16 v[92:95], v[162:165], v[200:203], v[92:95]
	v_mfma_f32_16x16x32_bf16 v[88:91], v[162:165], v[208:211], v[88:91]
	v_mfma_f32_16x16x32_bf16 v[84:87], v[170:173], v[200:203], v[84:87]
	v_mfma_f32_16x16x32_bf16 v[80:83], v[170:173], v[208:211], v[80:83]
	v_mfma_f32_16x16x32_bf16 v[76:79], v[178:181], v[200:203], v[76:79]
	v_mfma_f32_16x16x32_bf16 v[72:75], v[178:181], v[208:211], v[72:75]
	v_mfma_f32_16x16x32_bf16 v[68:71], v[186:189], v[200:203], v[68:71]
	v_mfma_f32_16x16x32_bf16 v[64:67], v[186:189], v[208:211], v[64:67]
	v_mfma_f32_16x16x32_bf16 v[92:95], v[166:169], v[204:207], v[92:95]
	v_mfma_f32_16x16x32_bf16 v[88:91], v[166:169], v[212:215], v[88:91]
	v_mfma_f32_16x16x32_bf16 v[84:87], v[174:177], v[204:207], v[84:87]
	v_mfma_f32_16x16x32_bf16 v[80:83], v[174:177], v[212:215], v[80:83]
	v_mfma_f32_16x16x32_bf16 v[76:79], v[182:185], v[204:207], v[76:79]
	v_mfma_f32_16x16x32_bf16 v[72:75], v[182:185], v[212:215], v[72:75]
	v_mfma_f32_16x16x32_bf16 v[68:71], v[196:199], v[204:207], v[68:71]
	v_mfma_f32_16x16x32_bf16 v[64:67], v[196:199], v[212:215], v[64:67]
	s_add_u32 s75, s40, s48
	s_addc_u32 s78, s41, s49
	s_add_u32 s54, s75, 0x100
	s_addc_u32 s55, s78, 0
	v_lshl_add_u64 v[190:191], s[54:55], 0, v[192:193]
	v_readfirstlane_b32 s54, v130
	s_mov_b32 m0, s54
	v_readfirstlane_b32 s54, v131
	s_barrier
	ds_read_b128 v[162:165], v195 offset:16384
	ds_read_b128 v[166:169], v195 offset:17408
	ds_read_b128 v[170:173], v195 offset:18432
	ds_read_b128 v[174:177], v195 offset:19456
	ds_read_b128 v[178:181], v195 offset:20480
	ds_read_b128 v[182:185], v195 offset:21504
	ds_read_b128 v[186:189], v195 offset:22528
	ds_read_b128 v[196:199], v195 offset:23552
	global_load_lds_dwordx4 v[190:191], off
	v_lshl_add_u64 v[190:191], v[190:191], 0, s[34:35]
	s_mov_b32 m0, s54
	s_nop 0
	global_load_lds_dwordx4 v[190:191], off
	s_barrier
	s_waitcnt lgkmcnt(0)
	s_waitcnt lgkmcnt(0)
	v_mfma_f32_16x16x32_bf16 v[60:63], v[162:165], v[146:149], v[60:63]
	v_mfma_f32_16x16x32_bf16 v[56:59], v[162:165], v[154:157], v[56:59]
	v_mfma_f32_16x16x32_bf16 v[52:55], v[170:173], v[146:149], v[52:55]
	v_mfma_f32_16x16x32_bf16 v[48:51], v[170:173], v[154:157], v[48:51]
	v_mfma_f32_16x16x32_bf16 v[44:47], v[178:181], v[146:149], v[44:47]
	v_mfma_f32_16x16x32_bf16 v[40:43], v[178:181], v[154:157], v[40:43]
	v_mfma_f32_16x16x32_bf16 v[36:39], v[186:189], v[146:149], v[36:39]
	v_mfma_f32_16x16x32_bf16 v[32:35], v[186:189], v[154:157], v[32:35]
	v_mfma_f32_16x16x32_bf16 v[60:63], v[166:169], v[150:153], v[60:63]
	v_mfma_f32_16x16x32_bf16 v[56:59], v[166:169], v[158:161], v[56:59]
	v_mfma_f32_16x16x32_bf16 v[52:55], v[174:177], v[150:153], v[52:55]
	v_mfma_f32_16x16x32_bf16 v[48:51], v[174:177], v[158:161], v[48:51]
	v_mfma_f32_16x16x32_bf16 v[44:47], v[182:185], v[150:153], v[44:47]
	v_mfma_f32_16x16x32_bf16 v[40:43], v[182:185], v[158:161], v[40:43]
	v_mfma_f32_16x16x32_bf16 v[36:39], v[196:199], v[150:153], v[36:39]
	v_mfma_f32_16x16x32_bf16 v[32:35], v[196:199], v[158:161], v[32:35]
	s_barrier
	s_add_u32 s79, s44, s48
	s_addc_u32 s80, s45, s49
	s_add_u32 s54, s79, 0x100
	s_addc_u32 s55, s80, 0
	v_lshl_add_u64 v[146:147], s[54:55], 0, v[192:193]
	v_readfirstlane_b32 s54, v132
	s_mov_b32 m0, s54
	v_readfirstlane_b32 s54, v133
	global_load_lds_dwordx4 v[146:147], off
	v_lshl_add_u64 v[146:147], v[146:147], 0, s[34:35]
	s_mov_b32 m0, s54
	s_nop 0
	global_load_lds_dwordx4 v[146:147], off
	s_waitcnt vmcnt(6)
	s_barrier
	v_mfma_f32_16x16x32_bf16 v[28:31], v[162:165], v[200:203], v[28:31]
	v_mfma_f32_16x16x32_bf16 v[24:27], v[162:165], v[208:211], v[24:27]
	v_mfma_f32_16x16x32_bf16 v[20:23], v[170:173], v[200:203], v[20:23]
	v_mfma_f32_16x16x32_bf16 v[16:19], v[170:173], v[208:211], v[16:19]
	v_mfma_f32_16x16x32_bf16 v[12:15], v[178:181], v[200:203], v[12:15]
	v_mfma_f32_16x16x32_bf16 v[8:11], v[178:181], v[208:211], v[8:11]
	v_mfma_f32_16x16x32_bf16 v[4:7], v[186:189], v[200:203], v[4:7]
	v_mfma_f32_16x16x32_bf16 v[0:3], v[186:189], v[208:211], v[0:3]
	v_mfma_f32_16x16x32_bf16 v[28:31], v[166:169], v[204:207], v[28:31]
	v_mfma_f32_16x16x32_bf16 v[24:27], v[166:169], v[212:215], v[24:27]
	v_mfma_f32_16x16x32_bf16 v[20:23], v[174:177], v[204:207], v[20:23]
	v_mfma_f32_16x16x32_bf16 v[16:19], v[174:177], v[212:215], v[16:19]
	v_mfma_f32_16x16x32_bf16 v[12:15], v[182:185], v[204:207], v[12:15]
	v_mfma_f32_16x16x32_bf16 v[8:11], v[182:185], v[212:215], v[8:11]
	v_mfma_f32_16x16x32_bf16 v[4:7], v[196:199], v[204:207], v[4:7]
	v_mfma_f32_16x16x32_bf16 v[0:3], v[196:199], v[212:215], v[0:3]
	v_add_u32_e32 v145, s93, v136
	s_barrier
	ds_read_b128 v[146:149], v145
	ds_read_b128 v[150:153], v145 offset:1024
	ds_read_b128 v[154:157], v145 offset:2048
	ds_read_b128 v[158:161], v145 offset:3072
	s_add_u32 s54, s13, 0x100
	s_addc_u32 s55, s72, 0
	v_readfirstlane_b32 s13, v134
	v_lshl_add_u64 v[190:191], s[54:55], 0, v[192:193]
	s_mov_b32 m0, s13
	v_readfirstlane_b32 s13, v135
	ds_read_b128 v[162:165], v195 offset:32768
	ds_read_b128 v[166:169], v195 offset:33792
	ds_read_b128 v[170:173], v195 offset:34816
	ds_read_b128 v[174:177], v195 offset:35840
	ds_read_b128 v[178:181], v195 offset:36864
	ds_read_b128 v[182:185], v195 offset:37888
	ds_read_b128 v[186:189], v195 offset:38912
	ds_read_b128 v[196:199], v195 offset:39936
	global_load_lds_dwordx4 v[190:191], off
	v_lshl_add_u64 v[190:191], v[190:191], 0, s[34:35]
	s_mov_b32 m0, s13
	s_nop 0
	global_load_lds_dwordx4 v[190:191], off
	s_waitcnt lgkmcnt(8)
	s_barrier
	s_waitcnt lgkmcnt(0)
	s_waitcnt lgkmcnt(0)
	v_mfma_f32_16x16x32_bf16 v[124:127], v[162:165], v[146:149], v[124:127]
	v_mfma_f32_16x16x32_bf16 v[120:123], v[162:165], v[154:157], v[120:123]
	v_mfma_f32_16x16x32_bf16 v[116:119], v[170:173], v[146:149], v[116:119]
	v_mfma_f32_16x16x32_bf16 v[112:115], v[170:173], v[154:157], v[112:115]
	v_mfma_f32_16x16x32_bf16 v[108:111], v[178:181], v[146:149], v[108:111]
	v_mfma_f32_16x16x32_bf16 v[104:107], v[178:181], v[154:157], v[104:107]
	v_mfma_f32_16x16x32_bf16 v[100:103], v[186:189], v[146:149], v[100:103]
	v_mfma_f32_16x16x32_bf16 v[96:99], v[186:189], v[154:157], v[96:99]
	v_mfma_f32_16x16x32_bf16 v[124:127], v[166:169], v[150:153], v[124:127]
	v_mfma_f32_16x16x32_bf16 v[120:123], v[166:169], v[158:161], v[120:123]
	v_mfma_f32_16x16x32_bf16 v[116:119], v[174:177], v[150:153], v[116:119]
	v_mfma_f32_16x16x32_bf16 v[112:115], v[174:177], v[158:161], v[112:115]
	v_mfma_f32_16x16x32_bf16 v[108:111], v[182:185], v[150:153], v[108:111]
	v_mfma_f32_16x16x32_bf16 v[104:107], v[182:185], v[158:161], v[104:107]
	v_mfma_f32_16x16x32_bf16 v[100:103], v[196:199], v[150:153], v[100:103]
	v_mfma_f32_16x16x32_bf16 v[96:99], v[196:199], v[158:161], v[96:99]
	s_barrier
	s_add_u32 s54, s73, 0x180
	s_addc_u32 s55, s74, 0
	v_readfirstlane_b32 s13, v137
	v_add_u32_e32 v145, s89, v136
	v_lshl_add_u64 v[190:191], s[54:55], 0, v[192:193]
	s_mov_b32 m0, s13
	v_readfirstlane_b32 s13, v138
	ds_read_b128 v[200:203], v145
	ds_read_b128 v[204:207], v145 offset:1024
	ds_read_b128 v[208:211], v145 offset:2048
	ds_read_b128 v[212:215], v145 offset:3072
	global_load_lds_dwordx4 v[190:191], off
	v_lshl_add_u64 v[190:191], v[190:191], 0, s[34:35]
	s_mov_b32 m0, s13
	s_nop 0
	global_load_lds_dwordx4 v[190:191], off
	s_barrier
	s_waitcnt lgkmcnt(0)
	s_waitcnt lgkmcnt(0)
	v_mfma_f32_16x16x32_bf16 v[92:95], v[162:165], v[200:203], v[92:95]
	v_mfma_f32_16x16x32_bf16 v[88:91], v[162:165], v[208:211], v[88:91]
	v_mfma_f32_16x16x32_bf16 v[84:87], v[170:173], v[200:203], v[84:87]
	v_mfma_f32_16x16x32_bf16 v[80:83], v[170:173], v[208:211], v[80:83]
	v_mfma_f32_16x16x32_bf16 v[76:79], v[178:181], v[200:203], v[76:79]
	v_mfma_f32_16x16x32_bf16 v[72:75], v[178:181], v[208:211], v[72:75]
	v_mfma_f32_16x16x32_bf16 v[68:71], v[186:189], v[200:203], v[68:71]
	v_mfma_f32_16x16x32_bf16 v[64:67], v[186:189], v[208:211], v[64:67]
	v_mfma_f32_16x16x32_bf16 v[92:95], v[166:169], v[204:207], v[92:95]
	v_mfma_f32_16x16x32_bf16 v[88:91], v[166:169], v[212:215], v[88:91]
	v_mfma_f32_16x16x32_bf16 v[84:87], v[174:177], v[204:207], v[84:87]
	v_mfma_f32_16x16x32_bf16 v[80:83], v[174:177], v[212:215], v[80:83]
	v_mfma_f32_16x16x32_bf16 v[76:79], v[182:185], v[204:207], v[76:79]
	v_mfma_f32_16x16x32_bf16 v[72:75], v[182:185], v[212:215], v[72:75]
	v_mfma_f32_16x16x32_bf16 v[68:71], v[196:199], v[204:207], v[68:71]
	v_mfma_f32_16x16x32_bf16 v[64:67], v[196:199], v[212:215], v[64:67]
	s_add_u32 s54, s75, 0x180
	s_addc_u32 s55, s78, 0
	v_readfirstlane_b32 s13, v139
	v_lshl_add_u64 v[190:191], s[54:55], 0, v[192:193]
	s_mov_b32 m0, s13
	v_readfirstlane_b32 s13, v140
	s_barrier
	ds_read_b128 v[162:165], v195 offset:49152
	ds_read_b128 v[166:169], v195 offset:50176
	ds_read_b128 v[170:173], v195 offset:51200
	ds_read_b128 v[174:177], v195 offset:52224
	ds_read_b128 v[178:181], v195 offset:53248
	ds_read_b128 v[182:185], v195 offset:54272
	ds_read_b128 v[186:189], v195 offset:55296
	ds_read_b128 v[196:199], v195 offset:56320
	global_load_lds_dwordx4 v[190:191], off
	v_lshl_add_u64 v[190:191], v[190:191], 0, s[34:35]
	s_mov_b32 m0, s13
	s_nop 0
	global_load_lds_dwordx4 v[190:191], off
	s_barrier
	s_waitcnt lgkmcnt(0)
	s_waitcnt lgkmcnt(0)
	v_mfma_f32_16x16x32_bf16 v[60:63], v[162:165], v[146:149], v[60:63]
	v_mfma_f32_16x16x32_bf16 v[56:59], v[162:165], v[154:157], v[56:59]
	v_mfma_f32_16x16x32_bf16 v[52:55], v[170:173], v[146:149], v[52:55]
	v_mfma_f32_16x16x32_bf16 v[48:51], v[170:173], v[154:157], v[48:51]
	v_mfma_f32_16x16x32_bf16 v[44:47], v[178:181], v[146:149], v[44:47]
	v_mfma_f32_16x16x32_bf16 v[40:43], v[178:181], v[154:157], v[40:43]
	v_mfma_f32_16x16x32_bf16 v[36:39], v[186:189], v[146:149], v[36:39]
	v_mfma_f32_16x16x32_bf16 v[32:35], v[186:189], v[154:157], v[32:35]
	v_mfma_f32_16x16x32_bf16 v[60:63], v[166:169], v[150:153], v[60:63]
	v_mfma_f32_16x16x32_bf16 v[56:59], v[166:169], v[158:161], v[56:59]
	v_mfma_f32_16x16x32_bf16 v[52:55], v[174:177], v[150:153], v[52:55]
	v_mfma_f32_16x16x32_bf16 v[48:51], v[174:177], v[158:161], v[48:51]
	v_mfma_f32_16x16x32_bf16 v[44:47], v[182:185], v[150:153], v[44:47]
	v_mfma_f32_16x16x32_bf16 v[40:43], v[182:185], v[158:161], v[40:43]
	v_mfma_f32_16x16x32_bf16 v[36:39], v[196:199], v[150:153], v[36:39]
	v_mfma_f32_16x16x32_bf16 v[32:35], v[196:199], v[158:161], v[32:35]
	s_barrier
	s_add_u32 s54, s79, 0x180
	s_addc_u32 s55, s80, 0
	v_readfirstlane_b32 s13, v141
	v_lshl_add_u64 v[146:147], s[54:55], 0, v[192:193]
	s_mov_b32 m0, s13
	v_readfirstlane_b32 s13, v142
	global_load_lds_dwordx4 v[146:147], off
	v_lshl_add_u64 v[146:147], v[146:147], 0, s[34:35]
	s_mov_b32 m0, s13
	s_nop 0
	global_load_lds_dwordx4 v[146:147], off
	s_waitcnt vmcnt(6)
	s_barrier
	v_mfma_f32_16x16x32_bf16 v[28:31], v[162:165], v[200:203], v[28:31]
	v_mfma_f32_16x16x32_bf16 v[24:27], v[162:165], v[208:211], v[24:27]
	v_mfma_f32_16x16x32_bf16 v[20:23], v[170:173], v[200:203], v[20:23]
	v_mfma_f32_16x16x32_bf16 v[16:19], v[170:173], v[208:211], v[16:19]
	v_mfma_f32_16x16x32_bf16 v[12:15], v[178:181], v[200:203], v[12:15]
	v_mfma_f32_16x16x32_bf16 v[8:11], v[178:181], v[208:211], v[8:11]
	v_mfma_f32_16x16x32_bf16 v[4:7], v[186:189], v[200:203], v[4:7]
	v_mfma_f32_16x16x32_bf16 v[0:3], v[186:189], v[208:211], v[0:3]
	v_mfma_f32_16x16x32_bf16 v[28:31], v[166:169], v[204:207], v[28:31]
	v_mfma_f32_16x16x32_bf16 v[24:27], v[166:169], v[212:215], v[24:27]
	v_mfma_f32_16x16x32_bf16 v[20:23], v[174:177], v[204:207], v[20:23]
	v_mfma_f32_16x16x32_bf16 v[16:19], v[174:177], v[212:215], v[16:19]
	v_mfma_f32_16x16x32_bf16 v[12:15], v[182:185], v[204:207], v[12:15]
	v_mfma_f32_16x16x32_bf16 v[8:11], v[182:185], v[212:215], v[8:11]
	v_mfma_f32_16x16x32_bf16 v[4:7], v[196:199], v[204:207], v[4:7]
	v_mfma_f32_16x16x32_bf16 v[0:3], v[196:199], v[212:215], v[0:3]
	s_add_i32 s3, s3, 2
	s_add_u32 s48, s48, 0x100
	s_addc_u32 s49, s49, 0
	s_cmp_lt_u32 s3, 12
	s_barrier
	s_cbranch_scc1 .LBB0_1020
	v_add_u32_e32 v190, 0, v136
	s_add_u32 s38, s46, 0x780
	v_add_u32_e32 v140, 0x10000, v190
	s_addc_u32 s39, s47, 0
	v_readfirstlane_b32 s3, v143
	ds_read_b128 v[128:131], v140
	ds_read_b128 v[132:135], v140 offset:1024
	ds_read_b128 v[136:139], v140 offset:2048
	ds_read_b128 v[146:149], v140 offset:3072
	ds_read_b128 v[150:153], v195
	ds_read_b128 v[154:157], v195 offset:1024
	ds_read_b128 v[158:161], v195 offset:2048
	ds_read_b128 v[162:165], v195 offset:3072
	ds_read_b128 v[166:169], v195 offset:4096
	ds_read_b128 v[170:173], v195 offset:5120
	ds_read_b128 v[174:177], v195 offset:6144
	ds_read_b128 v[178:181], v195 offset:7168
	v_lshl_add_u64 v[140:141], s[38:39], 0, v[192:193]
	s_mov_b32 m0, s3
	v_readfirstlane_b32 s3, v144
	global_load_lds_dwordx4 v[140:141], off
	v_lshl_add_u64 v[140:141], v[140:141], 0, s[34:35]
	s_mov_b32 m0, s3
	s_nop 0
	global_load_lds_dwordx4 v[140:141], off
	s_barrier
	s_waitcnt lgkmcnt(0)
	s_waitcnt lgkmcnt(0)
	v_mfma_f32_16x16x32_bf16 v[124:127], v[150:153], v[128:131], v[124:127]
	v_mfma_f32_16x16x32_bf16 v[120:123], v[150:153], v[136:139], v[120:123]
	v_mfma_f32_16x16x32_bf16 v[116:119], v[158:161], v[128:131], v[116:119]
	v_mfma_f32_16x16x32_bf16 v[112:115], v[158:161], v[136:139], v[112:115]
	v_mfma_f32_16x16x32_bf16 v[108:111], v[166:169], v[128:131], v[108:111]
	v_mfma_f32_16x16x32_bf16 v[104:107], v[166:169], v[136:139], v[104:107]
	v_mfma_f32_16x16x32_bf16 v[100:103], v[174:177], v[128:131], v[100:103]
	v_mfma_f32_16x16x32_bf16 v[96:99], v[174:177], v[136:139], v[96:99]
	v_mfma_f32_16x16x32_bf16 v[124:127], v[154:157], v[132:135], v[124:127]
	v_mfma_f32_16x16x32_bf16 v[120:123], v[154:157], v[146:149], v[120:123]
	v_mfma_f32_16x16x32_bf16 v[116:119], v[162:165], v[132:135], v[116:119]
	v_mfma_f32_16x16x32_bf16 v[112:115], v[162:165], v[146:149], v[112:115]
	v_mfma_f32_16x16x32_bf16 v[108:111], v[170:173], v[132:135], v[108:111]
	v_mfma_f32_16x16x32_bf16 v[104:107], v[170:173], v[146:149], v[104:107]
	v_mfma_f32_16x16x32_bf16 v[100:103], v[178:181], v[132:135], v[100:103]
	v_mfma_f32_16x16x32_bf16 v[96:99], v[178:181], v[146:149], v[96:99]
	v_add_u32_e32 v144, 0x14000, v190
	s_barrier
	ds_read_b128 v[140:143], v144
	ds_read_b128 v[182:185], v144 offset:1024
	ds_read_b128 v[186:189], v144 offset:2048
	ds_read_b128 v[196:199], v144 offset:3072
	s_barrier
	s_waitcnt lgkmcnt(0)
	s_waitcnt lgkmcnt(0)
	v_mfma_f32_16x16x32_bf16 v[92:95], v[150:153], v[140:143], v[92:95]
	v_mfma_f32_16x16x32_bf16 v[88:91], v[150:153], v[186:189], v[88:91]
	v_mfma_f32_16x16x32_bf16 v[84:87], v[158:161], v[140:143], v[84:87]
	v_mfma_f32_16x16x32_bf16 v[80:83], v[158:161], v[186:189], v[80:83]
	v_mfma_f32_16x16x32_bf16 v[76:79], v[166:169], v[140:143], v[76:79]
	v_mfma_f32_16x16x32_bf16 v[72:75], v[166:169], v[186:189], v[72:75]
	v_mfma_f32_16x16x32_bf16 v[68:71], v[174:177], v[140:143], v[68:71]
	v_mfma_f32_16x16x32_bf16 v[64:67], v[174:177], v[186:189], v[64:67]
	v_mfma_f32_16x16x32_bf16 v[92:95], v[154:157], v[182:185], v[92:95]
	v_mfma_f32_16x16x32_bf16 v[88:91], v[154:157], v[196:199], v[88:91]
	v_mfma_f32_16x16x32_bf16 v[84:87], v[162:165], v[182:185], v[84:87]
	v_mfma_f32_16x16x32_bf16 v[80:83], v[162:165], v[196:199], v[80:83]
	v_mfma_f32_16x16x32_bf16 v[76:79], v[170:173], v[182:185], v[76:79]
	v_mfma_f32_16x16x32_bf16 v[72:75], v[170:173], v[196:199], v[72:75]
	v_mfma_f32_16x16x32_bf16 v[68:71], v[178:181], v[182:185], v[68:71]
	v_mfma_f32_16x16x32_bf16 v[64:67], v[178:181], v[196:199], v[64:67]
	s_barrier
	ds_read_b128 v[150:153], v195 offset:16384
	ds_read_b128 v[154:157], v195 offset:17408
	ds_read_b128 v[158:161], v195 offset:18432
	ds_read_b128 v[162:165], v195 offset:19456
	ds_read_b128 v[166:169], v195 offset:20480
	ds_read_b128 v[170:173], v195 offset:21504
	ds_read_b128 v[174:177], v195 offset:22528
	ds_read_b128 v[178:181], v195 offset:23552
	s_waitcnt vmcnt(4)
	s_barrier
	s_waitcnt lgkmcnt(0)
	s_waitcnt lgkmcnt(0)
	v_mfma_f32_16x16x32_bf16 v[60:63], v[150:153], v[128:131], v[60:63]
	v_mfma_f32_16x16x32_bf16 v[56:59], v[150:153], v[136:139], v[56:59]
	v_mfma_f32_16x16x32_bf16 v[52:55], v[158:161], v[128:131], v[52:55]
	v_mfma_f32_16x16x32_bf16 v[48:51], v[158:161], v[136:139], v[48:51]
	v_mfma_f32_16x16x32_bf16 v[44:47], v[166:169], v[128:131], v[44:47]
	v_mfma_f32_16x16x32_bf16 v[40:43], v[166:169], v[136:139], v[40:43]
	v_mfma_f32_16x16x32_bf16 v[36:39], v[174:177], v[128:131], v[36:39]
	v_mfma_f32_16x16x32_bf16 v[32:35], v[174:177], v[136:139], v[32:35]
	v_mfma_f32_16x16x32_bf16 v[60:63], v[154:157], v[132:135], v[60:63]
	v_mfma_f32_16x16x32_bf16 v[56:59], v[154:157], v[146:149], v[56:59]
	v_mfma_f32_16x16x32_bf16 v[52:55], v[162:165], v[132:135], v[52:55]
	v_mfma_f32_16x16x32_bf16 v[48:51], v[162:165], v[146:149], v[48:51]
	v_mfma_f32_16x16x32_bf16 v[44:47], v[170:173], v[132:135], v[44:47]
	v_mfma_f32_16x16x32_bf16 v[40:43], v[170:173], v[146:149], v[40:43]
	v_mfma_f32_16x16x32_bf16 v[36:39], v[178:181], v[132:135], v[36:39]
	v_mfma_f32_16x16x32_bf16 v[32:35], v[178:181], v[146:149], v[32:35]
	v_mfma_f32_16x16x32_bf16 v[28:31], v[150:153], v[140:143], v[28:31]
	v_mfma_f32_16x16x32_bf16 v[24:27], v[150:153], v[186:189], v[24:27]
	v_mfma_f32_16x16x32_bf16 v[20:23], v[158:161], v[140:143], v[20:23]
	v_mfma_f32_16x16x32_bf16 v[16:19], v[158:161], v[186:189], v[16:19]
	v_mfma_f32_16x16x32_bf16 v[12:15], v[166:169], v[140:143], v[12:15]
	v_mfma_f32_16x16x32_bf16 v[8:11], v[166:169], v[186:189], v[8:11]
	v_mfma_f32_16x16x32_bf16 v[4:7], v[174:177], v[140:143], v[4:7]
	v_mfma_f32_16x16x32_bf16 v[0:3], v[174:177], v[186:189], v[0:3]
	v_mfma_f32_16x16x32_bf16 v[200:203], v[154:157], v[182:185], v[28:31]
	v_mfma_f32_16x16x32_bf16 v[204:207], v[154:157], v[196:199], v[24:27]
	v_mfma_f32_16x16x32_bf16 v[208:211], v[162:165], v[182:185], v[20:23]
	v_mfma_f32_16x16x32_bf16 v[212:215], v[162:165], v[196:199], v[16:19]
	v_mfma_f32_16x16x32_bf16 v[216:219], v[170:173], v[182:185], v[12:15]
	v_mfma_f32_16x16x32_bf16 v[220:223], v[170:173], v[196:199], v[8:11]
	v_mfma_f32_16x16x32_bf16 v[224:227], v[178:181], v[182:185], v[4:7]
	v_mfma_f32_16x16x32_bf16 v[196:199], v[178:181], v[196:199], v[0:3]
	s_nop 1
	v_add_u32_e32 v0, 0x18000, v190
	s_barrier
	ds_read_b128 v[24:27], v0
	ds_read_b128 v[28:31], v0 offset:1024
	ds_read_b128 v[228:231], v0 offset:2048
	ds_read_b128 v[240:243], v0 offset:3072
	ds_read_b128 v[0:3], v195 offset:32768
	ds_read_b128 v[4:7], v195 offset:33792
	ds_read_b128 v[8:11], v195 offset:34816
	ds_read_b128 v[12:15], v195 offset:35840
	ds_read_b128 v[16:19], v195 offset:36864
	ds_read_b128 v[20:23], v195 offset:37888
	ds_read_b128 v[184:187], v195 offset:38912
	ds_read_b128 v[248:251], v195 offset:39936
	s_waitcnt vmcnt(2)
	s_barrier
	s_waitcnt lgkmcnt(0)
	s_waitcnt lgkmcnt(0)
	v_mfma_f32_16x16x32_bf16 v[124:127], v[0:3], v[24:27], v[124:127]
	v_mfma_f32_16x16x32_bf16 v[120:123], v[0:3], v[228:231], v[120:123]
	v_mfma_f32_16x16x32_bf16 v[116:119], v[8:11], v[24:27], v[116:119]
	v_mfma_f32_16x16x32_bf16 v[112:115], v[8:11], v[228:231], v[112:115]
	v_mfma_f32_16x16x32_bf16 v[108:111], v[16:19], v[24:27], v[108:111]
	v_mfma_f32_16x16x32_bf16 v[104:107], v[16:19], v[228:231], v[104:107]
	v_mfma_f32_16x16x32_bf16 v[100:103], v[184:187], v[24:27], v[100:103]
	v_mfma_f32_16x16x32_bf16 v[96:99], v[184:187], v[228:231], v[96:99]
	v_mfma_f32_16x16x32_bf16 v[156:159], v[4:7], v[28:31], v[124:127]
	v_mfma_f32_16x16x32_bf16 v[128:131], v[4:7], v[240:243], v[120:123]
	v_mfma_f32_16x16x32_bf16 v[132:135], v[12:15], v[28:31], v[116:119]
	v_mfma_f32_16x16x32_bf16 v[136:139], v[12:15], v[240:243], v[112:115]
	v_mfma_f32_16x16x32_bf16 v[140:143], v[20:23], v[28:31], v[108:111]
	v_mfma_f32_16x16x32_bf16 v[144:147], v[20:23], v[240:243], v[104:107]
	v_mfma_f32_16x16x32_bf16 v[148:151], v[248:251], v[28:31], v[100:103]
	v_mfma_f32_16x16x32_bf16 v[152:155], v[248:251], v[240:243], v[96:99]
	v_add_u32_e32 v108, 0x1c000, v190
	s_barrier
	ds_read_b128 v[96:99], v108
	ds_read_b128 v[100:103], v108 offset:1024
	ds_read_b128 v[104:107], v108 offset:2048
	ds_read_b128 v[108:111], v108 offset:3072
	s_waitcnt vmcnt(0)
	s_barrier
	s_waitcnt lgkmcnt(0)
	s_waitcnt lgkmcnt(0)
	v_mfma_f32_16x16x32_bf16 v[92:95], v[0:3], v[96:99], v[92:95]
	v_mfma_f32_16x16x32_bf16 v[0:3], v[0:3], v[104:107], v[88:91]
	v_mfma_f32_16x16x32_bf16 v[160:163], v[4:7], v[108:111], v[0:3]
	v_mfma_f32_16x16x32_bf16 v[0:3], v[8:11], v[96:99], v[84:87]
	v_mfma_f32_16x16x32_bf16 v[164:167], v[12:15], v[100:103], v[0:3]
	v_mfma_f32_16x16x32_bf16 v[0:3], v[8:11], v[104:107], v[80:83]
	v_mfma_f32_16x16x32_bf16 v[168:171], v[12:15], v[108:111], v[0:3]
	v_mfma_f32_16x16x32_bf16 v[0:3], v[16:19], v[96:99], v[76:79]
	v_mfma_f32_16x16x32_bf16 v[172:175], v[20:23], v[100:103], v[0:3]
	v_mfma_f32_16x16x32_bf16 v[0:3], v[16:19], v[104:107], v[72:75]
	v_mfma_f32_16x16x32_bf16 v[176:179], v[20:23], v[108:111], v[0:3]
	v_mfma_f32_16x16x32_bf16 v[0:3], v[184:187], v[96:99], v[68:71]
	v_mfma_f32_16x16x32_bf16 v[180:183], v[248:251], v[100:103], v[0:3]
	v_mfma_f32_16x16x32_bf16 v[0:3], v[184:187], v[104:107], v[64:67]
	v_mfma_f32_16x16x32_bf16 v[188:191], v[4:7], v[100:103], v[92:95]
	v_mfma_f32_16x16x32_bf16 v[184:187], v[248:251], v[108:111], v[0:3]
	s_barrier
	ds_read_b128 v[64:67], v195 offset:49152
	ds_read_b128 v[68:71], v195 offset:50176
	ds_read_b128 v[72:75], v195 offset:51200
	ds_read_b128 v[76:79], v195 offset:52224
	ds_read_b128 v[80:83], v195 offset:53248
	ds_read_b128 v[84:87], v195 offset:54272
	ds_read_b128 v[88:91], v195 offset:55296
	ds_read_b128 v[92:95], v195 offset:56320
	s_barrier
	s_waitcnt lgkmcnt(0)
	s_waitcnt lgkmcnt(0)
	v_mfma_f32_16x16x32_bf16 v[0:3], v[64:67], v[24:27], v[60:63]
	v_mfma_f32_16x16x32_bf16 v[8:11], v[72:75], v[24:27], v[52:55]
	v_mfma_f32_16x16x32_bf16 v[16:19], v[80:83], v[24:27], v[44:47]
	v_mfma_f32_16x16x32_bf16 v[24:27], v[88:91], v[24:27], v[36:39]
	v_mfma_f32_16x16x32_bf16 v[0:3], v[68:71], v[28:31], v[0:3]
	v_mfma_f32_16x16x32_bf16 v[4:7], v[64:67], v[228:231], v[56:59]
	v_mfma_f32_16x16x32_bf16 v[8:11], v[76:79], v[28:31], v[8:11]
	v_mfma_f32_16x16x32_bf16 v[12:15], v[72:75], v[228:231], v[48:51]
	v_mfma_f32_16x16x32_bf16 v[16:19], v[84:87], v[28:31], v[16:19]
	v_mfma_f32_16x16x32_bf16 v[20:23], v[80:83], v[228:231], v[40:43]
	v_mfma_f32_16x16x32_bf16 v[24:27], v[92:95], v[28:31], v[24:27]
	v_mfma_f32_16x16x32_bf16 v[28:31], v[88:91], v[228:231], v[32:35]
	v_mfma_f32_16x16x32_bf16 v[4:7], v[68:71], v[240:243], v[4:7]
	v_mfma_f32_16x16x32_bf16 v[12:15], v[76:79], v[240:243], v[12:15]
	v_mfma_f32_16x16x32_bf16 v[20:23], v[84:87], v[240:243], v[20:23]
	v_mfma_f32_16x16x32_bf16 v[28:31], v[92:95], v[240:243], v[28:31]
	v_mfma_f32_16x16x32_bf16 v[32:35], v[64:67], v[96:99], v[200:203]
	v_mfma_f32_16x16x32_bf16 v[36:39], v[64:67], v[104:107], v[204:207]
	v_mfma_f32_16x16x32_bf16 v[40:43], v[72:75], v[96:99], v[208:211]
	v_mfma_f32_16x16x32_bf16 v[44:47], v[72:75], v[104:107], v[212:215]
	v_mfma_f32_16x16x32_bf16 v[48:51], v[80:83], v[96:99], v[216:219]
	v_mfma_f32_16x16x32_bf16 v[52:55], v[80:83], v[104:107], v[220:223]
	v_mfma_f32_16x16x32_bf16 v[56:59], v[88:91], v[96:99], v[224:227]
	v_mfma_f32_16x16x32_bf16 v[60:63], v[88:91], v[104:107], v[196:199]
	v_mfma_f32_16x16x32_bf16 v[32:35], v[68:71], v[100:103], v[32:35]
	v_mfma_f32_16x16x32_bf16 v[36:39], v[68:71], v[108:111], v[36:39]
	v_mfma_f32_16x16x32_bf16 v[40:43], v[76:79], v[100:103], v[40:43]
	v_mfma_f32_16x16x32_bf16 v[44:47], v[76:79], v[108:111], v[44:47]
	v_mfma_f32_16x16x32_bf16 v[48:51], v[84:87], v[100:103], v[48:51]
	v_mfma_f32_16x16x32_bf16 v[52:55], v[84:87], v[108:111], v[52:55]
	v_mfma_f32_16x16x32_bf16 v[56:59], v[92:95], v[100:103], v[56:59]
	v_mfma_f32_16x16x32_bf16 v[60:63], v[92:95], v[108:111], v[60:63]
	s_cmpk_gt_u32 s53, 0xff
	s_barrier
	s_cbranch_scc1 .LBB0_1023
	s_barrier
